# compress K-loop with 4 k-steps of loads in flight; attention FAR64 QK K-fragment reads issued 8-10 ahead; pass-3 stage resequencing
# speedup vs baseline: 1.0014x; 1.0014x over previous
; #define CP_LOAD(buf, s_) do { const int kabs_ = 512 * wid + 32 * (s_) + 8 * q; fa[buf] = *(const bf16x8*)(arow + (size_t)(kabs_ >> 7) * NPROJ + (kabs_ & 127)); \
;         _Pragma("unroll") for (int ct = 0; ct < 8; ++ct) fb[buf][ct] = *(const bf16x8*)(w1t + (size_t)(ct * 16 + r) * 4096 + kabs_); } while (0)
; DI void compress_item(const Params& P, int item, unsigned char* smem) {
;     ...
;     const int grow = rt * 16 + r, bg = grow / 127, c = grow % 127, b = bg >> 1, g = bg & 1;
;     const bf16_t* arow = proj + (size_t)(b * TT + 16 * c) * NPROJ + (which ? C_VC : C_KC) + g * 128;
;     f32x4 acc[8];
; #pragma unroll
;     for (int ct = 0; ct < 8; ++ct) acc[ct] = (f32x4){0.f, 0.f, 0.f, 0.f};
;     bf16x8 fa[2], fb[2][8];
;     ...
;     CP_LOAD(0, 0);
; #pragma unroll
;     for (int s = 0; s < 16; ++s) {
;         if (s + 1 < 16) CP_LOAD((s + 1) & 1, s + 1);
;         __builtin_amdgcn_sched_barrier(0);
; #pragma unroll
;         for (int ct = 0; ct < 8; ++ct) acc[ct] = __builtin_amdgcn_mfma_f32_16x16x32_bf16(fa[s & 1], fb[s & 1][ct], acc[ct], 0, 0, 0);
;         __builtin_amdgcn_sched_barrier(0);
;     }
.LBB0_637:
	s_andn2_b64 vcc, exec, s[4:5]
	s_cbranch_vccnz .LBB0_634
	s_mul_hi_i32 s4, s71, 0x81020409
	s_add_i32 s4, s4, s71
	s_lshr_b32 s5, s4, 31
	s_ashr_i32 s4, s4, 6
	s_add_i32 s72, s4, s5
	s_mul_i32 s73, s72, 0xfffff810
	v_add_u32_e32 v2, s33, v1
	v_add_u32_e32 v3, s73, v2
	v_mul_hi_i32 v4, v3, s59
	v_add_u32_e32 v3, v4, v3
	s_add_i32 s14, s71, 0x7e
	v_lshrrev_b32_e32 v4, 31, v3
	v_ashrrev_i32_e32 v3, 6, v3
	s_cmpk_gt_u32 s14, 0xfc
	v_add_u32_e32 v4, v3, v4
	s_cselect_b64 s[46:47], -1, 0
	s_lshl_b32 s4, s72, 7
	v_mul_lo_u32 v3, v4, s68
	s_mulk_i32 s72, 0x7f0
	v_subrev_u32_e32 v3, s72, v3
	s_ashr_i32 s5, s4, 31
	v_add_u32_e32 v2, v2, v3
	v_lshlrev_b32_e32 v3, 10, v4
	s_cmpk_lt_u32 s14, 0xfd
	v_and_b32_e32 v3, 0xfffff800, v3
	v_readlane_b32 s80, v245, 5
	s_cselect_b32 s76, s60, 0x9e00000
	v_lshl_add_u32 v5, v2, 4, v3
	v_readlane_b32 s82, v245, 7
	v_mov_b64_e32 v[2:3], s[12:13]
	s_cselect_b32 s14, s61, 0x9f08000
	s_cselect_b32 s74, s69, 0xa00
	s_mov_b32 s75, s15
	v_readlane_b32 s83, v245, 8
	s_add_u32 s76, s82, s76
	v_mad_i64_i32 v[2:3], s[78:79], v5, s53, v[2:3]
	v_lshlrev_b32_e32 v4, 8, v4
	s_addc_u32 s77, s83, 0
	v_lshl_add_u64 v[2:3], v[2:3], 0, s[74:75]
	v_and_b32_e32 v46, 0x100, v4
	v_mov_b32_e32 v59, v47
	v_lshl_add_u64 v[6:7], v[2:3], 0, v[46:47]
	v_mov_b32_e32 v55, v47
	v_lshl_add_u64 v[2:3], s[76:77], 0, v[58:59]
	v_lshl_add_u64 v[44:45], v[6:7], 0, v[54:55]
	v_mov_b32_e32 v57, v47
	v_mov_b32_e32 v63, v47
	v_mov_b32_e32 v65, v47
	v_mov_b32_e32 v67, v47
	v_mov_b32_e32 v69, v47
	v_mov_b32_e32 v71, v47
	v_mov_b32_e32 v73, v47
	v_mov_b32_e32 v75, v47
	v_mov_b32_e32 v77, v47
	v_lshl_add_u64 v[124:125], v[2:3], 0, 64
	v_lshl_add_u64 v[8:9], v[44:45], 0, v[56:57]
	v_mov_b32_e32 v61, v47
	v_lshl_add_u64 v[40:41], v[2:3], 0, v[62:63]
	v_lshl_add_u64 v[16:17], v[2:3], 0, v[64:65]
	v_lshl_add_u64 v[20:21], v[2:3], 0, v[66:67]
	v_lshl_add_u64 v[24:25], v[2:3], 0, v[68:69]
	v_lshl_add_u64 v[28:29], v[2:3], 0, v[70:71]
	v_lshl_add_u64 v[32:33], v[2:3], 0, v[72:73]
	v_lshl_add_u64 v[36:37], v[2:3], 0, v[74:75]
	v_lshl_add_u64 v[88:89], v[44:45], 0, v[76:77]
	v_lshl_add_u64 v[104:105], v[124:125], 0, v[62:63]
	v_lshl_add_u64 v[4:5], v[2:3], 0, v[60:61]
	v_readlane_b32 s81, v245, 6
	v_readlane_b32 s84, v245, 9
	v_readlane_b32 s85, v245, 10
	v_readlane_b32 s86, v245, 11
	v_readlane_b32 s87, v245, 12
	v_mov_b32_e32 v79, v47
	v_mov_b32_e32 v81, v47
	v_mov_b32_e32 v83, v47
	v_mov_b32_e32 v85, v47
	v_mov_b32_e32 v87, v47
	v_lshl_add_u64 v[34:35], v[6:7], 0, v[56:57]
	v_mov_b64_e32 v[36:37], v[2:3]
	v_lshl_add_u64 v[96:97], v[34:35], 0, v[54:55]
	global_load_dwordx4 v[96:99], v[96:97], off
	v_lshl_add_u64 v[100:101], v[36:37], 0, v[60:61]
	global_load_dwordx4 v[100:103], v[100:101], off
	v_lshl_add_u64 v[104:105], v[36:37], 0, v[62:63]
	global_load_dwordx4 v[104:107], v[104:105], off
	v_lshl_add_u64 v[108:109], v[36:37], 0, v[64:65]
	global_load_dwordx4 v[108:111], v[108:109], off
	v_lshl_add_u64 v[112:113], v[36:37], 0, v[66:67]
	global_load_dwordx4 v[112:115], v[112:113], off
	v_lshl_add_u64 v[116:117], v[36:37], 0, v[68:69]
	global_load_dwordx4 v[116:119], v[116:117], off
	v_lshl_add_u64 v[120:121], v[36:37], 0, v[70:71]
	global_load_dwordx4 v[120:123], v[120:121], off
	v_lshl_add_u64 v[124:125], v[36:37], 0, v[72:73]
	global_load_dwordx4 v[124:127], v[124:125], off
	v_lshl_add_u64 v[128:129], v[36:37], 0, v[74:75]
	global_load_dwordx4 v[128:131], v[128:129], off
	v_lshl_add_u64 v[132:133], v[34:35], 0, v[54:55]
	global_load_dwordx4 v[132:135], v[132:133], off offset:64
	v_lshl_add_u64 v[136:137], v[36:37], 0, v[60:61]
	global_load_dwordx4 v[136:139], v[136:137], off offset:64
	v_lshl_add_u64 v[140:141], v[36:37], 0, v[62:63]
	global_load_dwordx4 v[140:143], v[140:141], off offset:64
	v_lshl_add_u64 v[144:145], v[36:37], 0, v[64:65]
	global_load_dwordx4 v[144:147], v[144:145], off offset:64
	v_lshl_add_u64 v[148:149], v[36:37], 0, v[66:67]
	global_load_dwordx4 v[148:151], v[148:149], off offset:64
	v_lshl_add_u64 v[152:153], v[36:37], 0, v[68:69]
	global_load_dwordx4 v[152:155], v[152:153], off offset:64
	v_lshl_add_u64 v[156:157], v[36:37], 0, v[70:71]
	global_load_dwordx4 v[156:159], v[156:157], off offset:64
	v_lshl_add_u64 v[160:161], v[36:37], 0, v[72:73]
	global_load_dwordx4 v[160:163], v[160:161], off offset:64
	v_lshl_add_u64 v[164:165], v[36:37], 0, v[74:75]
	global_load_dwordx4 v[164:167], v[164:165], off offset:64
	v_lshl_add_u64 v[168:169], v[34:35], 0, v[54:55]
	global_load_dwordx4 v[168:171], v[168:169], off offset:128
	v_lshl_add_u64 v[172:173], v[36:37], 0, v[60:61]
	global_load_dwordx4 v[172:175], v[172:173], off offset:128
	v_lshl_add_u64 v[176:177], v[36:37], 0, v[62:63]
	global_load_dwordx4 v[176:179], v[176:177], off offset:128
	v_lshl_add_u64 v[180:181], v[36:37], 0, v[64:65]
	global_load_dwordx4 v[180:183], v[180:181], off offset:128
	v_lshl_add_u64 v[184:185], v[36:37], 0, v[66:67]
	global_load_dwordx4 v[184:187], v[184:185], off offset:128
	v_lshl_add_u64 v[188:189], v[36:37], 0, v[68:69]
	global_load_dwordx4 v[188:191], v[188:189], off offset:128
	v_lshl_add_u64 v[192:193], v[36:37], 0, v[70:71]
	global_load_dwordx4 v[192:195], v[192:193], off offset:128
	v_lshl_add_u64 v[196:197], v[36:37], 0, v[72:73]
	global_load_dwordx4 v[196:199], v[196:197], off offset:128
	v_lshl_add_u64 v[200:201], v[36:37], 0, v[74:75]
	global_load_dwordx4 v[200:203], v[200:201], off offset:128
	v_lshl_add_u64 v[208:209], v[34:35], 0, v[54:55]
	global_load_dwordx4 v[208:211], v[208:209], off offset:192
	v_lshl_add_u64 v[212:213], v[36:37], 0, v[60:61]
	global_load_dwordx4 v[212:215], v[212:213], off offset:192
	v_lshl_add_u64 v[216:217], v[36:37], 0, v[62:63]
	global_load_dwordx4 v[216:219], v[216:217], off offset:192
	v_lshl_add_u64 v[220:221], v[36:37], 0, v[64:65]
	global_load_dwordx4 v[220:223], v[220:221], off offset:192
	v_lshl_add_u64 v[224:225], v[36:37], 0, v[66:67]
	global_load_dwordx4 v[224:227], v[224:225], off offset:192
	v_lshl_add_u64 v[228:229], v[36:37], 0, v[68:69]
	global_load_dwordx4 v[228:231], v[228:229], off offset:192
	v_lshl_add_u64 v[232:233], v[36:37], 0, v[70:71]
	global_load_dwordx4 v[232:235], v[232:233], off offset:192
	v_lshl_add_u64 v[236:237], v[36:37], 0, v[72:73]
	global_load_dwordx4 v[236:239], v[236:237], off offset:192
	v_lshl_add_u64 v[240:241], v[36:37], 0, v[74:75]
	global_load_dwordx4 v[240:243], v[240:241], off offset:192
	s_waitcnt vmcnt(27)
; #define CP_LOAD(buf, s_) do { const int kabs_ = 512 * wid + 32 * (s_) + 8 * q; fa[buf] = *(const bf16x8*)(arow + (size_t)(kabs_ >> 7) * NPROJ + (kabs_ & 127)); \
;         _Pragma("unroll") for (int ct = 0; ct < 8; ++ct) fb[buf][ct] = *(const bf16x8*)(w1t + (size_t)(ct * 16 + r) * 4096 + kabs_); } while (0)
; DI void compress_item(const Params& P, int item, unsigned char* smem) {
;     ...
;     CP_LOAD(0, 0);
; #pragma unroll
;     for (int s = 0; s < 16; ++s) {
;         if (s + 1 < 16) CP_LOAD((s + 1) & 1, s + 1);
;         __builtin_amdgcn_sched_barrier(0);
; #pragma unroll
;         for (int ct = 0; ct < 8; ++ct) acc[ct] = __builtin_amdgcn_mfma_f32_16x16x32_bf16(fa[s & 1], fb[s & 1][ct], acc[ct], 0, 0, 0);
;         __builtin_amdgcn_sched_barrier(0);
;     }
	v_mfma_f32_16x16x32_bf16 v[2:5], v[96:99], v[100:103], 0
	v_mfma_f32_16x16x32_bf16 v[10:13], v[96:99], v[104:107], 0
	v_mfma_f32_16x16x32_bf16 v[14:17], v[96:99], v[108:111], 0
	v_mfma_f32_16x16x32_bf16 v[18:21], v[96:99], v[112:115], 0
	v_mfma_f32_16x16x32_bf16 v[22:25], v[96:99], v[116:119], 0
	v_mfma_f32_16x16x32_bf16 v[26:29], v[96:99], v[120:123], 0
	v_mfma_f32_16x16x32_bf16 v[30:33], v[96:99], v[124:127], 0
	v_mfma_f32_16x16x32_bf16 v[6:9], v[96:99], v[128:131], 0
	v_lshl_add_u64 v[96:97], v[34:35], 0, v[82:83]
	global_load_dwordx4 v[96:99], v[96:97], off
	v_lshl_add_u64 v[100:101], v[36:37], 0, v[60:61]
	global_load_dwordx4 v[100:103], v[100:101], off offset:256
	v_lshl_add_u64 v[104:105], v[36:37], 0, v[62:63]
	global_load_dwordx4 v[104:107], v[104:105], off offset:256
	v_lshl_add_u64 v[108:109], v[36:37], 0, v[64:65]
	global_load_dwordx4 v[108:111], v[108:109], off offset:256
	v_lshl_add_u64 v[112:113], v[36:37], 0, v[66:67]
	global_load_dwordx4 v[112:115], v[112:113], off offset:256
	v_lshl_add_u64 v[116:117], v[36:37], 0, v[68:69]
	global_load_dwordx4 v[116:119], v[116:117], off offset:256
	v_lshl_add_u64 v[120:121], v[36:37], 0, v[70:71]
	global_load_dwordx4 v[120:123], v[120:121], off offset:256
	v_lshl_add_u64 v[124:125], v[36:37], 0, v[72:73]
	global_load_dwordx4 v[124:127], v[124:125], off offset:256
	v_lshl_add_u64 v[128:129], v[36:37], 0, v[74:75]
	global_load_dwordx4 v[128:131], v[128:129], off offset:256
	s_waitcnt vmcnt(27)
	v_mfma_f32_16x16x32_bf16 v[2:5], v[132:135], v[136:139], v[2:5]
	v_mfma_f32_16x16x32_bf16 v[10:13], v[132:135], v[140:143], v[10:13]
	v_mfma_f32_16x16x32_bf16 v[14:17], v[132:135], v[144:147], v[14:17]
	v_mfma_f32_16x16x32_bf16 v[18:21], v[132:135], v[148:151], v[18:21]
	v_mfma_f32_16x16x32_bf16 v[22:25], v[132:135], v[152:155], v[22:25]
	v_mfma_f32_16x16x32_bf16 v[26:29], v[132:135], v[156:159], v[26:29]
	v_mfma_f32_16x16x32_bf16 v[30:33], v[132:135], v[160:163], v[30:33]
	v_mfma_f32_16x16x32_bf16 v[6:9], v[132:135], v[164:167], v[6:9]
	v_lshl_add_u64 v[132:133], v[34:35], 0, v[82:83]
	global_load_dwordx4 v[132:135], v[132:133], off offset:64
	v_lshl_add_u64 v[136:137], v[36:37], 0, v[60:61]
	global_load_dwordx4 v[136:139], v[136:137], off offset:320
	v_lshl_add_u64 v[140:141], v[36:37], 0, v[62:63]
	global_load_dwordx4 v[140:143], v[140:141], off offset:320
	v_lshl_add_u64 v[144:145], v[36:37], 0, v[64:65]
	global_load_dwordx4 v[144:147], v[144:145], off offset:320
	v_lshl_add_u64 v[148:149], v[36:37], 0, v[66:67]
	global_load_dwordx4 v[148:151], v[148:149], off offset:320
	v_lshl_add_u64 v[152:153], v[36:37], 0, v[68:69]
	global_load_dwordx4 v[152:155], v[152:153], off offset:320
	v_lshl_add_u64 v[156:157], v[36:37], 0, v[70:71]
	global_load_dwordx4 v[156:159], v[156:157], off offset:320
	v_lshl_add_u64 v[160:161], v[36:37], 0, v[72:73]
	global_load_dwordx4 v[160:163], v[160:161], off offset:320
	v_lshl_add_u64 v[164:165], v[36:37], 0, v[74:75]
	global_load_dwordx4 v[164:167], v[164:165], off offset:320
	s_waitcnt vmcnt(27)
	v_mfma_f32_16x16x32_bf16 v[2:5], v[168:171], v[172:175], v[2:5]
	v_mfma_f32_16x16x32_bf16 v[10:13], v[168:171], v[176:179], v[10:13]
	v_mfma_f32_16x16x32_bf16 v[14:17], v[168:171], v[180:183], v[14:17]
	v_mfma_f32_16x16x32_bf16 v[18:21], v[168:171], v[184:187], v[18:21]
	v_mfma_f32_16x16x32_bf16 v[22:25], v[168:171], v[188:191], v[22:25]
	v_mfma_f32_16x16x32_bf16 v[26:29], v[168:171], v[192:195], v[26:29]
	v_mfma_f32_16x16x32_bf16 v[30:33], v[168:171], v[196:199], v[30:33]
	v_mfma_f32_16x16x32_bf16 v[6:9], v[168:171], v[200:203], v[6:9]
	v_lshl_add_u64 v[168:169], v[34:35], 0, v[82:83]
	global_load_dwordx4 v[168:171], v[168:169], off offset:128
	v_lshl_add_u64 v[172:173], v[36:37], 0, v[60:61]
	global_load_dwordx4 v[172:175], v[172:173], off offset:384
	v_lshl_add_u64 v[176:177], v[36:37], 0, v[62:63]
	global_load_dwordx4 v[176:179], v[176:177], off offset:384
	v_lshl_add_u64 v[180:181], v[36:37], 0, v[64:65]
	global_load_dwordx4 v[180:183], v[180:181], off offset:384
	v_lshl_add_u64 v[184:185], v[36:37], 0, v[66:67]
	global_load_dwordx4 v[184:187], v[184:185], off offset:384
	v_lshl_add_u64 v[188:189], v[36:37], 0, v[68:69]
	global_load_dwordx4 v[188:191], v[188:189], off offset:384
	v_lshl_add_u64 v[192:193], v[36:37], 0, v[70:71]
	global_load_dwordx4 v[192:195], v[192:193], off offset:384
	v_lshl_add_u64 v[196:197], v[36:37], 0, v[72:73]
	global_load_dwordx4 v[196:199], v[196:197], off offset:384
	v_lshl_add_u64 v[200:201], v[36:37], 0, v[74:75]
	global_load_dwordx4 v[200:203], v[200:201], off offset:384
	s_waitcnt vmcnt(27)
	v_mfma_f32_16x16x32_bf16 v[2:5], v[208:211], v[212:215], v[2:5]
	v_mfma_f32_16x16x32_bf16 v[10:13], v[208:211], v[216:219], v[10:13]
	v_mfma_f32_16x16x32_bf16 v[14:17], v[208:211], v[220:223], v[14:17]
	v_mfma_f32_16x16x32_bf16 v[18:21], v[208:211], v[224:227], v[18:21]
	v_mfma_f32_16x16x32_bf16 v[22:25], v[208:211], v[228:231], v[22:25]
	v_mfma_f32_16x16x32_bf16 v[26:29], v[208:211], v[232:235], v[26:29]
	v_mfma_f32_16x16x32_bf16 v[30:33], v[208:211], v[236:239], v[30:33]
	v_mfma_f32_16x16x32_bf16 v[6:9], v[208:211], v[240:243], v[6:9]
	v_lshl_add_u64 v[208:209], v[34:35], 0, v[82:83]
	global_load_dwordx4 v[208:211], v[208:209], off offset:192
	v_lshl_add_u64 v[212:213], v[36:37], 0, v[60:61]
	global_load_dwordx4 v[212:215], v[212:213], off offset:448
	v_lshl_add_u64 v[216:217], v[36:37], 0, v[62:63]
	global_load_dwordx4 v[216:219], v[216:217], off offset:448
	v_lshl_add_u64 v[220:221], v[36:37], 0, v[64:65]
	global_load_dwordx4 v[220:223], v[220:221], off offset:448
	v_lshl_add_u64 v[224:225], v[36:37], 0, v[66:67]
	global_load_dwordx4 v[224:227], v[224:225], off offset:448
	v_lshl_add_u64 v[228:229], v[36:37], 0, v[68:69]
	global_load_dwordx4 v[228:231], v[228:229], off offset:448
	v_lshl_add_u64 v[232:233], v[36:37], 0, v[70:71]
	global_load_dwordx4 v[232:235], v[232:233], off offset:448
	v_lshl_add_u64 v[236:237], v[36:37], 0, v[72:73]
	global_load_dwordx4 v[236:239], v[236:237], off offset:448
	v_lshl_add_u64 v[240:241], v[36:37], 0, v[74:75]
	global_load_dwordx4 v[240:243], v[240:241], off offset:448
	s_waitcnt vmcnt(27)
; #define CP_LOAD(buf, s_) do { const int kabs_ = 512 * wid + 32 * (s_) + 8 * q; fa[buf] = *(const bf16x8*)(arow + (size_t)(kabs_ >> 7) * NPROJ + (kabs_ & 127)); \
;         _Pragma("unroll") for (int ct = 0; ct < 8; ++ct) fb[buf][ct] = *(const bf16x8*)(w1t + (size_t)(ct * 16 + r) * 4096 + kabs_); } while (0)
; DI void compress_item(const Params& P, int item, unsigned char* smem) {
;     ...
;     CP_LOAD(0, 0);
; #pragma unroll
;     for (int s = 0; s < 16; ++s) {
;         if (s + 1 < 16) CP_LOAD((s + 1) & 1, s + 1);
;         __builtin_amdgcn_sched_barrier(0);
; #pragma unroll
;         for (int ct = 0; ct < 8; ++ct) acc[ct] = __builtin_amdgcn_mfma_f32_16x16x32_bf16(fa[s & 1], fb[s & 1][ct], acc[ct], 0, 0, 0);
;         __builtin_amdgcn_sched_barrier(0);
;     }
	v_mfma_f32_16x16x32_bf16 v[2:5], v[96:99], v[100:103], v[2:5]
	v_mfma_f32_16x16x32_bf16 v[10:13], v[96:99], v[104:107], v[10:13]
	v_mfma_f32_16x16x32_bf16 v[14:17], v[96:99], v[108:111], v[14:17]
	v_mfma_f32_16x16x32_bf16 v[18:21], v[96:99], v[112:115], v[18:21]
	v_mfma_f32_16x16x32_bf16 v[22:25], v[96:99], v[116:119], v[22:25]
	v_mfma_f32_16x16x32_bf16 v[26:29], v[96:99], v[120:123], v[26:29]
	v_mfma_f32_16x16x32_bf16 v[30:33], v[96:99], v[124:127], v[30:33]
	v_mfma_f32_16x16x32_bf16 v[6:9], v[96:99], v[128:131], v[6:9]
	v_lshl_add_u64 v[96:97], v[34:35], 0, v[84:85]
	global_load_dwordx4 v[96:99], v[96:97], off
	v_lshl_add_u64 v[100:101], v[36:37], 0, v[60:61]
	global_load_dwordx4 v[100:103], v[100:101], off offset:512
	v_lshl_add_u64 v[104:105], v[36:37], 0, v[62:63]
	global_load_dwordx4 v[104:107], v[104:105], off offset:512
	v_lshl_add_u64 v[108:109], v[36:37], 0, v[64:65]
	global_load_dwordx4 v[108:111], v[108:109], off offset:512
	v_lshl_add_u64 v[112:113], v[36:37], 0, v[66:67]
	global_load_dwordx4 v[112:115], v[112:113], off offset:512
	v_lshl_add_u64 v[116:117], v[36:37], 0, v[68:69]
	global_load_dwordx4 v[116:119], v[116:117], off offset:512
	v_lshl_add_u64 v[120:121], v[36:37], 0, v[70:71]
	global_load_dwordx4 v[120:123], v[120:121], off offset:512
	v_lshl_add_u64 v[124:125], v[36:37], 0, v[72:73]
	global_load_dwordx4 v[124:127], v[124:125], off offset:512
	v_lshl_add_u64 v[128:129], v[36:37], 0, v[74:75]
	global_load_dwordx4 v[128:131], v[128:129], off offset:512
	s_waitcnt vmcnt(27)
	v_mfma_f32_16x16x32_bf16 v[2:5], v[132:135], v[136:139], v[2:5]
	v_mfma_f32_16x16x32_bf16 v[10:13], v[132:135], v[140:143], v[10:13]
	v_mfma_f32_16x16x32_bf16 v[14:17], v[132:135], v[144:147], v[14:17]
	v_mfma_f32_16x16x32_bf16 v[18:21], v[132:135], v[148:151], v[18:21]
	v_mfma_f32_16x16x32_bf16 v[22:25], v[132:135], v[152:155], v[22:25]
	v_mfma_f32_16x16x32_bf16 v[26:29], v[132:135], v[156:159], v[26:29]
	v_mfma_f32_16x16x32_bf16 v[30:33], v[132:135], v[160:163], v[30:33]
	v_mfma_f32_16x16x32_bf16 v[6:9], v[132:135], v[164:167], v[6:9]
	v_lshl_add_u64 v[132:133], v[34:35], 0, v[84:85]
	global_load_dwordx4 v[132:135], v[132:133], off offset:64
	v_lshl_add_u64 v[136:137], v[36:37], 0, v[60:61]
	global_load_dwordx4 v[136:139], v[136:137], off offset:576
	v_lshl_add_u64 v[140:141], v[36:37], 0, v[62:63]
	global_load_dwordx4 v[140:143], v[140:141], off offset:576
	v_lshl_add_u64 v[144:145], v[36:37], 0, v[64:65]
	global_load_dwordx4 v[144:147], v[144:145], off offset:576
	v_lshl_add_u64 v[148:149], v[36:37], 0, v[66:67]
	global_load_dwordx4 v[148:151], v[148:149], off offset:576
	v_lshl_add_u64 v[152:153], v[36:37], 0, v[68:69]
	global_load_dwordx4 v[152:155], v[152:153], off offset:576
	v_lshl_add_u64 v[156:157], v[36:37], 0, v[70:71]
	global_load_dwordx4 v[156:159], v[156:157], off offset:576
	v_lshl_add_u64 v[160:161], v[36:37], 0, v[72:73]
	global_load_dwordx4 v[160:163], v[160:161], off offset:576
	v_lshl_add_u64 v[164:165], v[36:37], 0, v[74:75]
	global_load_dwordx4 v[164:167], v[164:165], off offset:576
	s_waitcnt vmcnt(27)
	v_mfma_f32_16x16x32_bf16 v[2:5], v[168:171], v[172:175], v[2:5]
	v_mfma_f32_16x16x32_bf16 v[10:13], v[168:171], v[176:179], v[10:13]
	v_mfma_f32_16x16x32_bf16 v[14:17], v[168:171], v[180:183], v[14:17]
	v_mfma_f32_16x16x32_bf16 v[18:21], v[168:171], v[184:187], v[18:21]
	v_mfma_f32_16x16x32_bf16 v[22:25], v[168:171], v[188:191], v[22:25]
	v_mfma_f32_16x16x32_bf16 v[26:29], v[168:171], v[192:195], v[26:29]
	v_mfma_f32_16x16x32_bf16 v[30:33], v[168:171], v[196:199], v[30:33]
	v_mfma_f32_16x16x32_bf16 v[6:9], v[168:171], v[200:203], v[6:9]
	v_lshl_add_u64 v[168:169], v[34:35], 0, v[84:85]
	global_load_dwordx4 v[168:171], v[168:169], off offset:128
	v_lshl_add_u64 v[172:173], v[36:37], 0, v[60:61]
	global_load_dwordx4 v[172:175], v[172:173], off offset:640
	v_lshl_add_u64 v[176:177], v[36:37], 0, v[62:63]
	global_load_dwordx4 v[176:179], v[176:177], off offset:640
	v_lshl_add_u64 v[180:181], v[36:37], 0, v[64:65]
	global_load_dwordx4 v[180:183], v[180:181], off offset:640
	v_lshl_add_u64 v[184:185], v[36:37], 0, v[66:67]
	global_load_dwordx4 v[184:187], v[184:185], off offset:640
	v_lshl_add_u64 v[188:189], v[36:37], 0, v[68:69]
	global_load_dwordx4 v[188:191], v[188:189], off offset:640
	v_lshl_add_u64 v[192:193], v[36:37], 0, v[70:71]
	global_load_dwordx4 v[192:195], v[192:193], off offset:640
	v_lshl_add_u64 v[196:197], v[36:37], 0, v[72:73]
	global_load_dwordx4 v[196:199], v[196:197], off offset:640
	v_lshl_add_u64 v[200:201], v[36:37], 0, v[74:75]
	global_load_dwordx4 v[200:203], v[200:201], off offset:640
	s_waitcnt vmcnt(27)
	v_mfma_f32_16x16x32_bf16 v[2:5], v[208:211], v[212:215], v[2:5]
	v_mfma_f32_16x16x32_bf16 v[10:13], v[208:211], v[216:219], v[10:13]
	v_mfma_f32_16x16x32_bf16 v[14:17], v[208:211], v[220:223], v[14:17]
	v_mfma_f32_16x16x32_bf16 v[18:21], v[208:211], v[224:227], v[18:21]
	v_mfma_f32_16x16x32_bf16 v[22:25], v[208:211], v[228:231], v[22:25]
	v_mfma_f32_16x16x32_bf16 v[26:29], v[208:211], v[232:235], v[26:29]
	v_mfma_f32_16x16x32_bf16 v[30:33], v[208:211], v[236:239], v[30:33]
	v_mfma_f32_16x16x32_bf16 v[6:9], v[208:211], v[240:243], v[6:9]
	v_lshl_add_u64 v[208:209], v[34:35], 0, v[84:85]
	global_load_dwordx4 v[208:211], v[208:209], off offset:192
	v_lshl_add_u64 v[212:213], v[36:37], 0, v[60:61]
	global_load_dwordx4 v[212:215], v[212:213], off offset:704
	v_lshl_add_u64 v[216:217], v[36:37], 0, v[62:63]
	global_load_dwordx4 v[216:219], v[216:217], off offset:704
	v_lshl_add_u64 v[220:221], v[36:37], 0, v[64:65]
	global_load_dwordx4 v[220:223], v[220:221], off offset:704
	v_lshl_add_u64 v[224:225], v[36:37], 0, v[66:67]
	global_load_dwordx4 v[224:227], v[224:225], off offset:704
	v_lshl_add_u64 v[228:229], v[36:37], 0, v[68:69]
	global_load_dwordx4 v[228:231], v[228:229], off offset:704
	v_lshl_add_u64 v[232:233], v[36:37], 0, v[70:71]
	global_load_dwordx4 v[232:235], v[232:233], off offset:704
	v_lshl_add_u64 v[236:237], v[36:37], 0, v[72:73]
	global_load_dwordx4 v[236:239], v[236:237], off offset:704
	v_lshl_add_u64 v[240:241], v[36:37], 0, v[74:75]
	global_load_dwordx4 v[240:243], v[240:241], off offset:704
	s_waitcnt vmcnt(27)
; #define CP_LOAD(buf, s_) do { const int kabs_ = 512 * wid + 32 * (s_) + 8 * q; fa[buf] = *(const bf16x8*)(arow + (size_t)(kabs_ >> 7) * NPROJ + (kabs_ & 127)); \
;         _Pragma("unroll") for (int ct = 0; ct < 8; ++ct) fb[buf][ct] = *(const bf16x8*)(w1t + (size_t)(ct * 16 + r) * 4096 + kabs_); } while (0)
; DI void compress_item(const Params& P, int item, unsigned char* smem) {
;     ...
;     CP_LOAD(0, 0);
; #pragma unroll
;     for (int s = 0; s < 16; ++s) {
;         if (s + 1 < 16) CP_LOAD((s + 1) & 1, s + 1);
;         __builtin_amdgcn_sched_barrier(0);
; #pragma unroll
;         for (int ct = 0; ct < 8; ++ct) acc[ct] = __builtin_amdgcn_mfma_f32_16x16x32_bf16(fa[s & 1], fb[s & 1][ct], acc[ct], 0, 0, 0);
;         __builtin_amdgcn_sched_barrier(0);
;     }
	v_mfma_f32_16x16x32_bf16 v[2:5], v[96:99], v[100:103], v[2:5]
	v_mfma_f32_16x16x32_bf16 v[10:13], v[96:99], v[104:107], v[10:13]
	v_mfma_f32_16x16x32_bf16 v[14:17], v[96:99], v[108:111], v[14:17]
	v_mfma_f32_16x16x32_bf16 v[18:21], v[96:99], v[112:115], v[18:21]
	v_mfma_f32_16x16x32_bf16 v[22:25], v[96:99], v[116:119], v[22:25]
	v_mfma_f32_16x16x32_bf16 v[26:29], v[96:99], v[120:123], v[26:29]
	v_mfma_f32_16x16x32_bf16 v[30:33], v[96:99], v[124:127], v[30:33]
	v_mfma_f32_16x16x32_bf16 v[6:9], v[96:99], v[128:131], v[6:9]
	v_lshl_add_u64 v[96:97], v[34:35], 0, v[86:87]
	global_load_dwordx4 v[96:99], v[96:97], off
	v_lshl_add_u64 v[100:101], v[36:37], 0, v[60:61]
	global_load_dwordx4 v[100:103], v[100:101], off offset:768
	v_lshl_add_u64 v[104:105], v[36:37], 0, v[62:63]
	global_load_dwordx4 v[104:107], v[104:105], off offset:768
	v_lshl_add_u64 v[108:109], v[36:37], 0, v[64:65]
	global_load_dwordx4 v[108:111], v[108:109], off offset:768
	v_lshl_add_u64 v[112:113], v[36:37], 0, v[66:67]
	global_load_dwordx4 v[112:115], v[112:113], off offset:768
	v_lshl_add_u64 v[116:117], v[36:37], 0, v[68:69]
	global_load_dwordx4 v[116:119], v[116:117], off offset:768
	v_lshl_add_u64 v[120:121], v[36:37], 0, v[70:71]
	global_load_dwordx4 v[120:123], v[120:121], off offset:768
	v_lshl_add_u64 v[124:125], v[36:37], 0, v[72:73]
	global_load_dwordx4 v[124:127], v[124:125], off offset:768
	v_lshl_add_u64 v[128:129], v[36:37], 0, v[74:75]
	global_load_dwordx4 v[128:131], v[128:129], off offset:768
	s_waitcnt vmcnt(27)
	v_mfma_f32_16x16x32_bf16 v[2:5], v[132:135], v[136:139], v[2:5]
	v_mfma_f32_16x16x32_bf16 v[10:13], v[132:135], v[140:143], v[10:13]
	v_mfma_f32_16x16x32_bf16 v[14:17], v[132:135], v[144:147], v[14:17]
	v_mfma_f32_16x16x32_bf16 v[18:21], v[132:135], v[148:151], v[18:21]
	v_mfma_f32_16x16x32_bf16 v[22:25], v[132:135], v[152:155], v[22:25]
	v_mfma_f32_16x16x32_bf16 v[26:29], v[132:135], v[156:159], v[26:29]
	v_mfma_f32_16x16x32_bf16 v[30:33], v[132:135], v[160:163], v[30:33]
	v_mfma_f32_16x16x32_bf16 v[6:9], v[132:135], v[164:167], v[6:9]
	v_lshl_add_u64 v[132:133], v[34:35], 0, v[86:87]
	global_load_dwordx4 v[132:135], v[132:133], off offset:64
	v_lshl_add_u64 v[136:137], v[36:37], 0, v[60:61]
	global_load_dwordx4 v[136:139], v[136:137], off offset:832
	v_lshl_add_u64 v[140:141], v[36:37], 0, v[62:63]
	global_load_dwordx4 v[140:143], v[140:141], off offset:832
	v_lshl_add_u64 v[144:145], v[36:37], 0, v[64:65]
	global_load_dwordx4 v[144:147], v[144:145], off offset:832
	v_lshl_add_u64 v[148:149], v[36:37], 0, v[66:67]
	global_load_dwordx4 v[148:151], v[148:149], off offset:832
	v_lshl_add_u64 v[152:153], v[36:37], 0, v[68:69]
	global_load_dwordx4 v[152:155], v[152:153], off offset:832
	v_lshl_add_u64 v[156:157], v[36:37], 0, v[70:71]
	global_load_dwordx4 v[156:159], v[156:157], off offset:832
	v_lshl_add_u64 v[160:161], v[36:37], 0, v[72:73]
	global_load_dwordx4 v[160:163], v[160:161], off offset:832
	v_lshl_add_u64 v[164:165], v[36:37], 0, v[74:75]
	global_load_dwordx4 v[164:167], v[164:165], off offset:832
	s_waitcnt vmcnt(27)
	v_mfma_f32_16x16x32_bf16 v[2:5], v[168:171], v[172:175], v[2:5]
	v_mfma_f32_16x16x32_bf16 v[10:13], v[168:171], v[176:179], v[10:13]
	v_mfma_f32_16x16x32_bf16 v[14:17], v[168:171], v[180:183], v[14:17]
	v_mfma_f32_16x16x32_bf16 v[18:21], v[168:171], v[184:187], v[18:21]
	v_mfma_f32_16x16x32_bf16 v[22:25], v[168:171], v[188:191], v[22:25]
	v_mfma_f32_16x16x32_bf16 v[26:29], v[168:171], v[192:195], v[26:29]
	v_mfma_f32_16x16x32_bf16 v[30:33], v[168:171], v[196:199], v[30:33]
	v_mfma_f32_16x16x32_bf16 v[6:9], v[168:171], v[200:203], v[6:9]
	v_lshl_add_u64 v[168:169], v[34:35], 0, v[86:87]
	global_load_dwordx4 v[168:171], v[168:169], off offset:128
	v_lshl_add_u64 v[172:173], v[36:37], 0, v[60:61]
	global_load_dwordx4 v[172:175], v[172:173], off offset:896
	v_lshl_add_u64 v[176:177], v[36:37], 0, v[62:63]
	global_load_dwordx4 v[176:179], v[176:177], off offset:896
	v_lshl_add_u64 v[180:181], v[36:37], 0, v[64:65]
	global_load_dwordx4 v[180:183], v[180:181], off offset:896
	v_lshl_add_u64 v[184:185], v[36:37], 0, v[66:67]
	global_load_dwordx4 v[184:187], v[184:185], off offset:896
	v_lshl_add_u64 v[188:189], v[36:37], 0, v[68:69]
	global_load_dwordx4 v[188:191], v[188:189], off offset:896
	v_lshl_add_u64 v[192:193], v[36:37], 0, v[70:71]
	global_load_dwordx4 v[192:195], v[192:193], off offset:896
	v_lshl_add_u64 v[196:197], v[36:37], 0, v[72:73]
	global_load_dwordx4 v[196:199], v[196:197], off offset:896
	v_lshl_add_u64 v[200:201], v[36:37], 0, v[74:75]
	global_load_dwordx4 v[200:203], v[200:201], off offset:896
	s_waitcnt vmcnt(27)
	v_mfma_f32_16x16x32_bf16 v[2:5], v[208:211], v[212:215], v[2:5]
	v_mfma_f32_16x16x32_bf16 v[10:13], v[208:211], v[216:219], v[10:13]
	v_mfma_f32_16x16x32_bf16 v[14:17], v[208:211], v[220:223], v[14:17]
	v_mfma_f32_16x16x32_bf16 v[18:21], v[208:211], v[224:227], v[18:21]
	v_mfma_f32_16x16x32_bf16 v[22:25], v[208:211], v[228:231], v[22:25]
	v_mfma_f32_16x16x32_bf16 v[26:29], v[208:211], v[232:235], v[26:29]
	v_mfma_f32_16x16x32_bf16 v[30:33], v[208:211], v[236:239], v[30:33]
	v_mfma_f32_16x16x32_bf16 v[6:9], v[208:211], v[240:243], v[6:9]
	v_lshl_add_u64 v[208:209], v[34:35], 0, v[86:87]
	global_load_dwordx4 v[208:211], v[208:209], off offset:192
	v_lshl_add_u64 v[212:213], v[36:37], 0, v[60:61]
	global_load_dwordx4 v[212:215], v[212:213], off offset:960
	v_lshl_add_u64 v[216:217], v[36:37], 0, v[62:63]
	global_load_dwordx4 v[216:219], v[216:217], off offset:960
	v_lshl_add_u64 v[220:221], v[36:37], 0, v[64:65]
	global_load_dwordx4 v[220:223], v[220:221], off offset:960
	v_lshl_add_u64 v[224:225], v[36:37], 0, v[66:67]
	global_load_dwordx4 v[224:227], v[224:225], off offset:960
	v_lshl_add_u64 v[228:229], v[36:37], 0, v[68:69]
	global_load_dwordx4 v[228:231], v[228:229], off offset:960
	v_lshl_add_u64 v[232:233], v[36:37], 0, v[70:71]
	global_load_dwordx4 v[232:235], v[232:233], off offset:960
	v_lshl_add_u64 v[236:237], v[36:37], 0, v[72:73]
	global_load_dwordx4 v[236:239], v[236:237], off offset:960
	v_lshl_add_u64 v[240:241], v[36:37], 0, v[74:75]
	global_load_dwordx4 v[240:243], v[240:241], off offset:960
	s_waitcnt vmcnt(27)
; #define CP_LOAD(buf, s_) do { const int kabs_ = 512 * wid + 32 * (s_) + 8 * q; fa[buf] = *(const bf16x8*)(arow + (size_t)(kabs_ >> 7) * NPROJ + (kabs_ & 127)); \
;         _Pragma("unroll") for (int ct = 0; ct < 8; ++ct) fb[buf][ct] = *(const bf16x8*)(w1t + (size_t)(ct * 16 + r) * 4096 + kabs_); } while (0)
; DI void compress_item(const Params& P, int item, unsigned char* smem) {
;     ...
;     for (int s = 0; s < 16; ++s) {
;         if (s + 1 < 16) CP_LOAD((s + 1) & 1, s + 1);
;         __builtin_amdgcn_sched_barrier(0);
; #pragma unroll
;         for (int ct = 0; ct < 8; ++ct) acc[ct] = __builtin_amdgcn_mfma_f32_16x16x32_bf16(fa[s & 1], fb[s & 1][ct], acc[ct], 0, 0, 0);
;         __builtin_amdgcn_sched_barrier(0);
;     }
;     ...
; #pragma unroll
;     for (int ct = 0; ct < 8; ++ct)
; #pragma unroll
;         for (int j = 0; j < 4; ++j) part[(wid * 16 + 4 * q + j) * 128 + ct * 16 + r] = acc[ct][j];
;     __syncthreads();
	v_mfma_f32_16x16x32_bf16 v[2:5], v[96:99], v[100:103], v[2:5]
	v_mfma_f32_16x16x32_bf16 v[10:13], v[96:99], v[104:107], v[10:13]
	v_mfma_f32_16x16x32_bf16 v[14:17], v[96:99], v[108:111], v[14:17]
	v_mfma_f32_16x16x32_bf16 v[18:21], v[96:99], v[112:115], v[18:21]
	v_mfma_f32_16x16x32_bf16 v[22:25], v[96:99], v[116:119], v[22:25]
	v_mfma_f32_16x16x32_bf16 v[26:29], v[96:99], v[120:123], v[26:29]
	v_mfma_f32_16x16x32_bf16 v[30:33], v[96:99], v[124:127], v[30:33]
	v_mfma_f32_16x16x32_bf16 v[6:9], v[96:99], v[128:131], v[6:9]
	s_waitcnt vmcnt(18)
	v_mfma_f32_16x16x32_bf16 v[2:5], v[132:135], v[136:139], v[2:5]
	v_mfma_f32_16x16x32_bf16 v[10:13], v[132:135], v[140:143], v[10:13]
	v_mfma_f32_16x16x32_bf16 v[14:17], v[132:135], v[144:147], v[14:17]
	v_mfma_f32_16x16x32_bf16 v[18:21], v[132:135], v[148:151], v[18:21]
	v_mfma_f32_16x16x32_bf16 v[22:25], v[132:135], v[152:155], v[22:25]
	v_mfma_f32_16x16x32_bf16 v[26:29], v[132:135], v[156:159], v[26:29]
	v_mfma_f32_16x16x32_bf16 v[30:33], v[132:135], v[160:163], v[30:33]
	v_mfma_f32_16x16x32_bf16 v[6:9], v[132:135], v[164:167], v[6:9]
	s_waitcnt vmcnt(9)
	v_mfma_f32_16x16x32_bf16 v[2:5], v[168:171], v[172:175], v[2:5]
	v_mfma_f32_16x16x32_bf16 v[10:13], v[168:171], v[176:179], v[10:13]
	v_mfma_f32_16x16x32_bf16 v[14:17], v[168:171], v[180:183], v[14:17]
	v_mfma_f32_16x16x32_bf16 v[18:21], v[168:171], v[184:187], v[18:21]
	v_mfma_f32_16x16x32_bf16 v[22:25], v[168:171], v[188:191], v[22:25]
	v_mfma_f32_16x16x32_bf16 v[26:29], v[168:171], v[192:195], v[26:29]
	v_mfma_f32_16x16x32_bf16 v[30:33], v[168:171], v[196:199], v[30:33]
	v_mfma_f32_16x16x32_bf16 v[6:9], v[168:171], v[200:203], v[6:9]
	s_waitcnt vmcnt(0)
	v_mfma_f32_16x16x32_bf16 v[2:5], v[208:211], v[212:215], v[2:5]
	v_mfma_f32_16x16x32_bf16 v[10:13], v[208:211], v[216:219], v[10:13]
	v_mfma_f32_16x16x32_bf16 v[14:17], v[208:211], v[220:223], v[14:17]
	v_mfma_f32_16x16x32_bf16 v[18:21], v[208:211], v[224:227], v[18:21]
	v_mfma_f32_16x16x32_bf16 v[22:25], v[208:211], v[228:231], v[22:25]
	v_mfma_f32_16x16x32_bf16 v[26:29], v[208:211], v[232:235], v[26:29]
	v_mfma_f32_16x16x32_bf16 v[30:33], v[208:211], v[236:239], v[30:33]
	v_mfma_f32_16x16x32_bf16 v[6:9], v[208:211], v[240:243], v[6:9]
	s_nop 7
	s_nop 2
	ds_write2_b32 v95, v2, v10 offset1:16
	ds_write2_b32 v95, v3, v11 offset0:128 offset1:144
	v_add_u32_e32 v2, 0x400, v95
	ds_write2_b32 v2, v4, v12 offset1:16
	ds_write2_b32 v2, v5, v13 offset0:128 offset1:144
	ds_write2_b32 v95, v14, v18 offset0:32 offset1:48
	ds_write2_b32 v95, v15, v19 offset0:160 offset1:176
	ds_write2_b32 v2, v16, v20 offset0:32 offset1:48
	ds_write2_b32 v2, v17, v21 offset0:160 offset1:176
	ds_write2_b32 v95, v22, v26 offset0:64 offset1:80
	ds_write2_b32 v95, v23, v27 offset0:192 offset1:208
	ds_write2_b32 v2, v24, v28 offset0:64 offset1:80
	ds_write2_b32 v2, v25, v29 offset0:192 offset1:208
	ds_write2_b32 v95, v30, v6 offset0:96 offset1:112
	ds_write2_b32 v95, v31, v7 offset0:224 offset1:240
	ds_write2_b32 v2, v32, v8 offset0:96 offset1:112
	ds_write2_b32 v2, v33, v9 offset0:224 offset1:240
	v_lshl_add_u64 v[2:3], s[4:5], 2, v[48:49]
	s_waitcnt lgkmcnt(0)
	s_barrier
; DI unsigned pk2(float a, float b) { f32x2_t v = {a, b}; return __builtin_bit_cast(unsigned, __builtin_convertvector(v, bf16x2_t)); }
; DI float gelu_tanh(float v) { const float z = 0.7978845608028654f * (v + 0.044715f * v * v * v); const float th = 1.0f - 2.0f * __builtin_amdgcn_rcpf(__builtin_amdgcn_exp2f(2.8853900817779268f * z) + 1.0f); return 0.5f * v * (1.0f + th); }
; DI void compress_item(const Params& P, int item, unsigned char* smem) {
;     ...
;     { const int row = tid >> 5, c4 = (tid & 31) * 4; f32x4 s = *(const f32x4*)(cb1 + c4);
; #pragma unroll
;       for (int w = 0; w < 8; ++w) s += *(const f32x4*)(part + (w * 16 + row) * 128 + c4);
;       u32x2 o; o.x = pk2(gelu_tanh(s[0]), gelu_tanh(s[1])); o.y = pk2(gelu_tanh(s[2]), gelu_tanh(s[3]));
;       *(u32x2*)(hid + row * 136 + c4) = o; }
;     __syncthreads();
;     { f32x4 a2 = {0.f, 0.f, 0.f, 0.f};
; #pragma unroll
;       for (int s = 0; s < 4; ++s) { const bf16x8 a = *(const bf16x8*)(hid + r * 136 + 32 * s + 8 * q);
;           const bf16x8 bb = *(const bf16x8*)(w2t + (size_t)(16 * wid + r) * 128 + 32 * s + 8 * q);
;           a2 = __builtin_amdgcn_mfma_f32_16x16x32_bf16(a, bb, a2, 0, 0, 0); }
;       bf16_t* kcb = (bf16_t*)(ws + WS_KCB); bf16_t* vcbt = (bf16_t*)(ws + WS_VCBT);
; #pragma unroll
;       for (int j = 0; j < 4; ++j) { const int gr = rt * 16 + 4 * q + j, bg2 = gr / 127, c2 = gr % 127, col = 16 * wid + r;
;           const bf16_t v = (bf16_t)(pk2(a2[j], 0.f) & 0xffffu);
;           if (which == 0) kcb[(size_t)(bg2 * 128 + c2) * 128 + col] = v; else vcbt[(size_t)(bg2 * 128 + col) * 128 + c2] = v; } }
	global_load_dwordx4 v[2:5], v[2:3], off
	ds_read_b128 v[6:9], v91
	ds_read_b128 v[10:13], v91 offset:8192
	ds_read_b128 v[14:17], v91 offset:16384
	ds_read_b128 v[18:21], v91 offset:24576
	ds_read_b128 v[22:25], v91 offset:32768
	ds_read_b128 v[26:29], v91 offset:40960
	ds_read_b128 v[30:33], v91 offset:49152
	ds_read_b128 v[34:37], v91 offset:57344
	v_lshl_add_u64 v[38:39], v[50:51], 0, s[14:15]
	s_mov_b64 s[4:5], -1
	s_and_b64 vcc, exec, s[46:47]
	s_waitcnt vmcnt(0) lgkmcnt(7)
	v_pk_add_f32 v[4:5], v[4:5], v[8:9]
	v_pk_add_f32 v[2:3], v[2:3], v[6:7]
	s_waitcnt lgkmcnt(6)
	v_pk_add_f32 v[4:5], v[4:5], v[12:13]
	v_pk_add_f32 v[2:3], v[2:3], v[10:11]
	s_waitcnt lgkmcnt(5)
	v_pk_add_f32 v[4:5], v[4:5], v[16:17]
	v_pk_add_f32 v[2:3], v[2:3], v[14:15]
	s_waitcnt lgkmcnt(4)
	v_pk_add_f32 v[4:5], v[4:5], v[20:21]
	v_pk_add_f32 v[2:3], v[2:3], v[18:19]
	s_waitcnt lgkmcnt(3)
	v_pk_add_f32 v[4:5], v[4:5], v[24:25]
	v_pk_add_f32 v[2:3], v[2:3], v[22:23]
	s_waitcnt lgkmcnt(2)
	v_pk_add_f32 v[4:5], v[4:5], v[28:29]
	v_pk_add_f32 v[2:3], v[2:3], v[26:27]
	s_waitcnt lgkmcnt(1)
	v_pk_add_f32 v[4:5], v[4:5], v[32:33]
	v_pk_add_f32 v[2:3], v[2:3], v[30:31]
	s_waitcnt lgkmcnt(0)
	v_pk_add_f32 v[4:5], v[4:5], v[36:37]
	v_pk_add_f32 v[2:3], v[2:3], v[34:35]
	v_mul_f32_e32 v8, 0x3d372713, v4
	v_mul_f32_e32 v6, 0x3d372713, v2
	v_mul_f32_e32 v7, 0x3d372713, v3
	v_mul_f32_e32 v9, 0x3d372713, v5
	v_mul_f32_e32 v6, v2, v6
	v_mul_f32_e32 v7, v3, v7
	v_mul_f32_e32 v8, v4, v8
	v_mul_f32_e32 v9, v5, v9
	v_fma_f32 v6, v2, v6, v2
	v_fma_f32 v7, v3, v7, v3
	v_fma_f32 v8, v4, v8, v4
	v_fma_f32 v9, v5, v9, v5
	v_mul_f32_e32 v6, 0x3f4c422a, v6
	v_mul_f32_e32 v7, 0x3f4c422a, v7
	v_mul_f32_e32 v8, 0x3f4c422a, v8
	v_mul_f32_e32 v9, 0x3f4c422a, v9
	v_mul_f32_e32 v6, 0x4038aa3b, v6
	v_mul_f32_e32 v7, 0x4038aa3b, v7
	v_mul_f32_e32 v8, 0x4038aa3b, v8
	v_mul_f32_e32 v9, 0x4038aa3b, v9
	v_exp_f32_e32 v6, v6
	v_exp_f32_e32 v7, v7
	v_exp_f32_e32 v8, v8
	v_exp_f32_e32 v9, v9
	v_add_f32_e32 v6, 1.0, v6
	v_add_f32_e32 v7, 1.0, v7
	v_add_f32_e32 v8, 1.0, v8
	v_add_f32_e32 v9, 1.0, v9
	v_rcp_f32_e32 v6, v6
	v_rcp_f32_e32 v7, v7
	v_rcp_f32_e32 v8, v8
	v_rcp_f32_e32 v9, v9
	v_pk_mul_f32 v[2:3], v[2:3], 0.5 op_sel_hi:[1,0]
	v_pk_fma_f32 v[6:7], v[6:7], 2.0, 1.0 op_sel_hi:[1,0,0] neg_lo:[1,0,0] neg_hi:[1,0,0]
	v_pk_mul_f32 v[4:5], v[4:5], 0.5 op_sel_hi:[1,0]
	v_pk_fma_f32 v[8:9], v[8:9], 2.0, 1.0 op_sel_hi:[1,0,0] neg_lo:[1,0,0] neg_hi:[1,0,0]
	v_pk_add_f32 v[6:7], v[6:7], 1.0 op_sel_hi:[1,0]
	v_pk_add_f32 v[8:9], v[8:9], 1.0 op_sel_hi:[1,0]
	v_pk_mul_f32 v[2:3], v[2:3], v[6:7]
	v_pk_mul_f32 v[4:5], v[4:5], v[8:9]
	v_cvt_pk_bf16_f32 v2, v2, v3
	v_cvt_pk_bf16_f32 v3, v4, v5
	ds_write_b64 v92, v[2:3]
	s_waitcnt lgkmcnt(0)
	s_barrier
	global_load_dwordx4 v[2:5], v[38:39], off
	global_load_dwordx4 v[8:11], v[38:39], off offset:64
	global_load_dwordx4 v[12:15], v[38:39], off offset:128
	global_load_dwordx4 v[16:19], v[38:39], off offset:192
	ds_read_b128 v[20:23], v93
	ds_read_b128 v[24:27], v93 offset:64
	ds_read_b128 v[28:31], v93 offset:128
	v_add_u32_e32 v7, s33, v90
	v_add_u32_e32 v6, s73, v7
	s_waitcnt vmcnt(3) lgkmcnt(2)
	v_mfma_f32_16x16x32_bf16 v[2:5], v[20:23], v[2:5], 0
	ds_read_b128 v[20:23], v93 offset:192
	s_waitcnt vmcnt(2) lgkmcnt(2)
	v_mfma_f32_16x16x32_bf16 v[2:5], v[24:27], v[8:11], v[2:5]
	v_mul_hi_i32 v8, v6, s59
	v_add_u32_e32 v8, v8, v6
	v_lshrrev_b32_e32 v9, 31, v8
	s_waitcnt vmcnt(1) lgkmcnt(1)
	v_mfma_f32_16x16x32_bf16 v[2:5], v[28:31], v[12:15], v[2:5]
	v_ashrrev_i32_e32 v8, 6, v8
	v_add_u32_e32 v8, v8, v9
	s_waitcnt vmcnt(0) lgkmcnt(0)
	v_mfma_f32_16x16x32_bf16 v[2:5], v[20:23], v[16:19], v[2:5]
	s_nop 7
	v_cvt_pk_bf16_f32 v2, v2, s0
	s_cbranch_vccz .LBB0_640
	v_mul_lo_u32 v9, v8, s68
	v_lshl_add_u32 v12, v8, 7, v94
	v_subrev_u32_e32 v9, s72, v9
	v_ashrrev_i32_e32 v13, 31, v12
	v_add_u32_e32 v10, v7, v9
	v_lshlrev_b64 v[12:13], 8, v[12:13]
	v_ashrrev_i32_e32 v11, 31, v10
	v_lshl_add_u64 v[12:13], s[10:11], 0, v[12:13]
	v_lshl_add_u64 v[10:11], v[10:11], 1, v[12:13]
	global_store_short v[10:11], v2, off
	s_mov_b64 s[4:5], 0

; DI float bf2f(unsigned x) { return __uint_as_float(x << 16); }
; DI void s5_bu16(const bf16x8 ub, const bf16x8 (&af)[8], float* buf, int r, int q) {
; #pragma unroll
;     for (int pt = 0; pt < 8; ++pt) { f32x4 d = {0.f, 0.f, 0.f, 0.f}; d = __builtin_amdgcn_mfma_f32_16x16x32_bf16(af[pt], ub, d, 0, 0, 0);
; #pragma unroll
;         for (int j = 0; j < 4; ++j) buf[(16 * pt + 4 * q + j) * 17 + r] = d[j]; }
; }
; DI void s5_pass3_item(const Params& P, int bitem, unsigned char* smem) {
;     ...
;     for (int sub = 0; sub < 4; ++sub) {
;         s5_bu16(ubs[sub], af, xs, r, q);
;         float uv[4];
; #pragma unroll
;         for (int j = 0; j < 4; ++j) uv[j] = bf2f(uvs[sub][j]);
;         asm volatile("s_waitcnt lgkmcnt(0)" ::: "memory");
; #pragma unroll
;         for (int tt = 0; tt < 16; ++tt) { const float bur = xs[lane * 17 + tt], bui = xs[(64 + lane) * 17 + tt];
;             const float nxr = ab[0] * xr - ab[1] * xi + bur, nxi = ab[0] * xi + ab[1] * xr + bui; xr = nxr; xi = nxi;
;             xs[lane * 17 + tt] = xr; xs[(64 + lane) * 17 + tt] = xi; }
.Ls5n_cdone:
	s_waitcnt lgkmcnt(0)
	s_mov_b64 s[28:29], s[26:27]
	v_mfma_f32_16x16x32_bf16 v[160:163], v[88:91], v[8:11], 0
	v_mfma_f32_16x16x32_bf16 v[164:167], v[88:91], v[12:15], 0
	v_mfma_f32_16x16x32_bf16 v[168:171], v[88:91], v[16:19], 0
	v_mfma_f32_16x16x32_bf16 v[172:175], v[88:91], v[20:23], 0
	v_mfma_f32_16x16x32_bf16 v[176:179], v[88:91], v[24:27], 0
	v_mfma_f32_16x16x32_bf16 v[180:183], v[88:91], v[28:31], 0
	v_mfma_f32_16x16x32_bf16 v[184:187], v[88:91], v[32:35], 0
	v_mfma_f32_16x16x32_bf16 v[188:191], v[88:91], v[36:39], 0
	s_nop 7
	v_permlane32_swap_b32_e32 v160, v168
	v_permlane32_swap_b32_e32 v161, v169
	v_permlane32_swap_b32_e32 v162, v170
	v_permlane32_swap_b32_e32 v163, v171
	v_permlane32_swap_b32_e32 v164, v172
	v_permlane32_swap_b32_e32 v165, v173
	v_permlane32_swap_b32_e32 v166, v174
	v_permlane32_swap_b32_e32 v167, v175
	v_permlane32_swap_b32_e32 v176, v184
	v_permlane32_swap_b32_e32 v177, v185
	v_permlane32_swap_b32_e32 v178, v186
	v_permlane32_swap_b32_e32 v179, v187
	v_permlane32_swap_b32_e32 v180, v188
	v_permlane32_swap_b32_e32 v181, v189
	v_permlane32_swap_b32_e32 v182, v190
	v_permlane32_swap_b32_e32 v183, v191
	v_permlane16_swap_b32_e32 v160, v164
	v_permlane16_swap_b32_e32 v161, v165
	v_permlane16_swap_b32_e32 v162, v166
	v_permlane16_swap_b32_e32 v163, v167
	v_permlane16_swap_b32_e32 v168, v172
	v_permlane16_swap_b32_e32 v169, v173
	v_permlane16_swap_b32_e32 v170, v174
	v_permlane16_swap_b32_e32 v171, v175
	v_permlane16_swap_b32_e32 v176, v180
	v_permlane16_swap_b32_e32 v177, v181
	v_permlane16_swap_b32_e32 v178, v182
	v_permlane16_swap_b32_e32 v179, v183
	v_permlane16_swap_b32_e32 v184, v188
	v_permlane16_swap_b32_e32 v185, v189
	v_permlane16_swap_b32_e32 v186, v190
	v_permlane16_swap_b32_e32 v187, v191
	v_mul_f32_e32 v194, v73, v193
	v_mul_f32_e32 v195, v73, v192
	v_fma_f32 v194, v72, v192, -v194
	v_fma_f32 v195, v72, v193, v195
	v_add_f32_e32 v160, v194, v160
	v_add_f32_e32 v176, v195, v176
	ds_write_addtid_b32 v160 offset:0
	ds_write_addtid_b32 v176 offset:256
	v_mul_f32_e32 v194, v73, v176
	v_mul_f32_e32 v195, v73, v160
	v_fma_f32 v194, v72, v160, -v194
	v_fma_f32 v195, v72, v176, v195
	v_add_f32_e32 v161, v194, v161
	v_add_f32_e32 v177, v195, v177
	ds_write_addtid_b32 v161 offset:528
	ds_write_addtid_b32 v177 offset:784
	v_mul_f32_e32 v194, v73, v177
	v_mul_f32_e32 v195, v73, v161
	v_fma_f32 v194, v72, v161, -v194
	v_fma_f32 v195, v72, v177, v195
	v_add_f32_e32 v162, v194, v162
	v_add_f32_e32 v178, v195, v178
	ds_write_addtid_b32 v162 offset:1056
	ds_write_addtid_b32 v178 offset:1312
	v_mul_f32_e32 v194, v73, v178
	v_mul_f32_e32 v195, v73, v162
	v_fma_f32 v194, v72, v162, -v194
	v_fma_f32 v195, v72, v178, v195
	v_add_f32_e32 v163, v194, v163
	v_add_f32_e32 v179, v195, v179
	ds_write_addtid_b32 v163 offset:1584
	ds_write_addtid_b32 v179 offset:1840
	v_mul_f32_e32 v194, v73, v179
	v_mul_f32_e32 v195, v73, v163
	v_fma_f32 v194, v72, v163, -v194
	v_fma_f32 v195, v72, v179, v195
	v_add_f32_e32 v164, v194, v164
	v_add_f32_e32 v180, v195, v180
	ds_write_addtid_b32 v164 offset:2112
	ds_write_addtid_b32 v180 offset:2368
	v_mul_f32_e32 v194, v73, v180
	v_mul_f32_e32 v195, v73, v164
	v_fma_f32 v194, v72, v164, -v194
	v_fma_f32 v195, v72, v180, v195
	v_add_f32_e32 v165, v194, v165
	v_add_f32_e32 v181, v195, v181
	ds_write_addtid_b32 v165 offset:2640
	ds_write_addtid_b32 v181 offset:2896
	v_mul_f32_e32 v194, v73, v181
	v_mul_f32_e32 v195, v73, v165
	v_fma_f32 v194, v72, v165, -v194
	v_fma_f32 v195, v72, v181, v195
	v_add_f32_e32 v166, v194, v166
	v_add_f32_e32 v182, v195, v182
	ds_write_addtid_b32 v166 offset:3168
	ds_write_addtid_b32 v182 offset:3424
	v_mul_f32_e32 v194, v73, v182
	v_mul_f32_e32 v195, v73, v166
	v_fma_f32 v194, v72, v166, -v194
	v_fma_f32 v195, v72, v182, v195
	v_add_f32_e32 v167, v194, v167
	v_add_f32_e32 v183, v195, v183
	ds_write_addtid_b32 v167 offset:3696
	ds_write_addtid_b32 v183 offset:3952
	v_mul_f32_e32 v194, v73, v183
	v_mul_f32_e32 v195, v73, v167
	v_fma_f32 v194, v72, v167, -v194
	v_fma_f32 v195, v72, v183, v195
	v_add_f32_e32 v168, v194, v168
	v_add_f32_e32 v184, v195, v184
	ds_write_addtid_b32 v168 offset:4224
	ds_write_addtid_b32 v184 offset:4480
	v_mul_f32_e32 v194, v73, v184
	v_mul_f32_e32 v195, v73, v168
	v_fma_f32 v194, v72, v168, -v194
	v_fma_f32 v195, v72, v184, v195
	v_add_f32_e32 v169, v194, v169
	v_add_f32_e32 v185, v195, v185
	ds_write_addtid_b32 v169 offset:4752
	ds_write_addtid_b32 v185 offset:5008
	v_mul_f32_e32 v194, v73, v185
	v_mul_f32_e32 v195, v73, v169
	v_fma_f32 v194, v72, v169, -v194
	v_fma_f32 v195, v72, v185, v195
	v_add_f32_e32 v170, v194, v170
	v_add_f32_e32 v186, v195, v186
	ds_write_addtid_b32 v170 offset:5280
	ds_write_addtid_b32 v186 offset:5536
	v_mul_f32_e32 v194, v73, v186
	v_mul_f32_e32 v195, v73, v170
	v_fma_f32 v194, v72, v170, -v194
	v_fma_f32 v195, v72, v186, v195
	v_add_f32_e32 v171, v194, v171
	v_add_f32_e32 v187, v195, v187
	ds_write_addtid_b32 v171 offset:5808
	ds_write_addtid_b32 v187 offset:6064
	v_mul_f32_e32 v194, v73, v187
	v_mul_f32_e32 v195, v73, v171
	v_fma_f32 v194, v72, v171, -v194
	v_fma_f32 v195, v72, v187, v195
	v_add_f32_e32 v172, v194, v172
	v_add_f32_e32 v188, v195, v188
	ds_write_addtid_b32 v172 offset:6336
	ds_write_addtid_b32 v188 offset:6592
	v_mul_f32_e32 v194, v73, v188
	v_mul_f32_e32 v195, v73, v172
	v_fma_f32 v194, v72, v172, -v194
	v_fma_f32 v195, v72, v188, v195
	v_add_f32_e32 v173, v194, v173
	v_add_f32_e32 v189, v195, v189
	ds_write_addtid_b32 v173 offset:6864
	ds_write_addtid_b32 v189 offset:7120
	v_mul_f32_e32 v194, v73, v189
	v_mul_f32_e32 v195, v73, v173
	v_fma_f32 v194, v72, v173, -v194
; DI void s5_pass3_item(const Params& P, int bitem, unsigned char* smem) {
;     ...
;         for (int tt = 0; tt < 16; ++tt) { const float bur = xs[lane * 17 + tt], bui = xs[(64 + lane) * 17 + tt];
;             const float nxr = ab[0] * xr - ab[1] * xi + bur, nxi = ab[0] * xi + ab[1] * xr + bui; xr = nxr; xi = nxi;
;             xs[lane * 17 + tt] = xr; xs[(64 + lane) * 17 + tt] = xi; }
;         asm volatile("s_waitcnt lgkmcnt(0)" ::: "memory");
;         f32x4 ya[4];
; #pragma unroll
;         for (int j = 0; j < 4; ++j) ya[j] = (f32x4){0.f, 0.f, 0.f, 0.f};
; #pragma unroll
;         for (int i = 0; i < 32; ++i) { const float a = xs[(4 * i + q) * 17 + r]; ya[i & 3] = __builtin_amdgcn_mfma_f32_16x16x4f32(a, cB[i], ya[i & 3], 0, 0, 0); }
	v_fma_f32 v195, v72, v189, v195
	v_add_f32_e32 v174, v194, v174
	v_add_f32_e32 v190, v195, v190
	ds_write_addtid_b32 v174 offset:7392
	ds_write_addtid_b32 v190 offset:7648
	v_mul_f32_e32 v194, v73, v190
	v_mul_f32_e32 v195, v73, v174
	v_fma_f32 v194, v72, v174, -v194
	v_fma_f32 v195, v72, v190, v195
	v_add_f32_e32 v175, v194, v175
	v_add_f32_e32 v191, v195, v191
	ds_write_addtid_b32 v175 offset:7920
	ds_write_addtid_b32 v191 offset:8176
	v_mov_b32_e32 v192, v175
	v_mov_b32_e32 v193, v191
	ds_read_b128 v[208:211], v77 offset:0
	ds_read_b128 v[212:215], v77 offset:64
	ds_read_b128 v[216:219], v77 offset:128
	ds_read_b128 v[220:223], v77 offset:192
	ds_read_b128 v[224:227], v77 offset:256
	ds_read_b128 v[228:231], v77 offset:320
	ds_read_b128 v[232:235], v77 offset:384
	ds_read_b128 v[236:239], v77 offset:448
	v_mfma_f32_16x16x32_bf16 v[160:163], v[92:95], v[8:11], 0
	v_mfma_f32_16x16x32_bf16 v[164:167], v[92:95], v[12:15], 0
	v_mfma_f32_16x16x32_bf16 v[168:171], v[92:95], v[16:19], 0
	v_mfma_f32_16x16x32_bf16 v[172:175], v[92:95], v[20:23], 0
	v_mfma_f32_16x16x32_bf16 v[176:179], v[92:95], v[24:27], 0
	v_mfma_f32_16x16x32_bf16 v[180:183], v[92:95], v[28:31], 0
	v_mfma_f32_16x16x32_bf16 v[184:187], v[92:95], v[32:35], 0
	v_mfma_f32_16x16x32_bf16 v[188:191], v[92:95], v[36:39], 0
	s_nop 7
	v_permlane32_swap_b32_e32 v160, v168
	v_permlane32_swap_b32_e32 v161, v169
	v_permlane32_swap_b32_e32 v162, v170
	v_permlane32_swap_b32_e32 v163, v171
	v_permlane32_swap_b32_e32 v164, v172
	v_permlane32_swap_b32_e32 v165, v173
	v_permlane32_swap_b32_e32 v166, v174
	v_permlane32_swap_b32_e32 v167, v175
	v_permlane32_swap_b32_e32 v176, v184
	v_permlane32_swap_b32_e32 v177, v185
	v_permlane32_swap_b32_e32 v178, v186
	v_permlane32_swap_b32_e32 v179, v187
	v_permlane32_swap_b32_e32 v180, v188
	v_permlane32_swap_b32_e32 v181, v189
	v_permlane32_swap_b32_e32 v182, v190
	v_permlane32_swap_b32_e32 v183, v191
	v_permlane16_swap_b32_e32 v160, v164
	v_permlane16_swap_b32_e32 v161, v165
	v_permlane16_swap_b32_e32 v162, v166
	v_permlane16_swap_b32_e32 v163, v167
	v_permlane16_swap_b32_e32 v168, v172
	v_permlane16_swap_b32_e32 v169, v173
	v_permlane16_swap_b32_e32 v170, v174
	v_permlane16_swap_b32_e32 v171, v175
	v_permlane16_swap_b32_e32 v176, v180
	v_permlane16_swap_b32_e32 v177, v181
	v_permlane16_swap_b32_e32 v178, v182
	v_permlane16_swap_b32_e32 v179, v183
	v_permlane16_swap_b32_e32 v184, v188
	v_permlane16_swap_b32_e32 v185, v189
	v_permlane16_swap_b32_e32 v186, v190
	v_permlane16_swap_b32_e32 v187, v191
	s_waitcnt lgkmcnt(7)
	v_mfma_f32_16x16x4_f32 v[200:203], v208, v40, 0
	s_waitcnt lgkmcnt(7)
	v_mfma_f32_16x16x4_f32 v[240:243], v209, v41, 0
	s_waitcnt lgkmcnt(7)
	v_mfma_f32_16x16x4_f32 v[200:203], v210, v42, v[200:203]
	s_waitcnt lgkmcnt(7)
	v_mfma_f32_16x16x4_f32 v[240:243], v211, v43, v[240:243]
	s_waitcnt lgkmcnt(6)
	v_mfma_f32_16x16x4_f32 v[200:203], v212, v44, v[200:203]
	s_waitcnt lgkmcnt(6)
	v_mfma_f32_16x16x4_f32 v[240:243], v213, v45, v[240:243]
	s_waitcnt lgkmcnt(6)
	v_mfma_f32_16x16x4_f32 v[200:203], v214, v46, v[200:203]
	s_waitcnt lgkmcnt(6)
	v_mfma_f32_16x16x4_f32 v[240:243], v215, v47, v[240:243]
	s_waitcnt lgkmcnt(5)
	v_mfma_f32_16x16x4_f32 v[200:203], v216, v48, v[200:203]
	s_waitcnt lgkmcnt(5)
	v_mfma_f32_16x16x4_f32 v[240:243], v217, v49, v[240:243]
	s_waitcnt lgkmcnt(5)
	v_mfma_f32_16x16x4_f32 v[200:203], v218, v50, v[200:203]
	s_waitcnt lgkmcnt(5)
	v_mfma_f32_16x16x4_f32 v[240:243], v219, v51, v[240:243]
	s_waitcnt lgkmcnt(4)
	v_mfma_f32_16x16x4_f32 v[200:203], v220, v52, v[200:203]
	s_waitcnt lgkmcnt(4)
	v_mfma_f32_16x16x4_f32 v[240:243], v221, v53, v[240:243]
	s_waitcnt lgkmcnt(4)
	v_mfma_f32_16x16x4_f32 v[200:203], v222, v54, v[200:203]
	s_waitcnt lgkmcnt(4)
	v_mfma_f32_16x16x4_f32 v[240:243], v223, v55, v[240:243]
	s_waitcnt lgkmcnt(3)
	v_mfma_f32_16x16x4_f32 v[200:203], v224, v56, v[200:203]
	s_waitcnt lgkmcnt(3)
	v_mfma_f32_16x16x4_f32 v[240:243], v225, v57, v[240:243]
	s_waitcnt lgkmcnt(3)
	v_mfma_f32_16x16x4_f32 v[200:203], v226, v58, v[200:203]
	s_waitcnt lgkmcnt(3)
	v_mfma_f32_16x16x4_f32 v[240:243], v227, v59, v[240:243]
	s_waitcnt lgkmcnt(2)
	v_mfma_f32_16x16x4_f32 v[200:203], v228, v60, v[200:203]
	s_waitcnt lgkmcnt(2)
	v_mfma_f32_16x16x4_f32 v[240:243], v229, v61, v[240:243]
	s_waitcnt lgkmcnt(2)
	v_mfma_f32_16x16x4_f32 v[200:203], v230, v62, v[200:203]
	s_waitcnt lgkmcnt(2)
	v_mfma_f32_16x16x4_f32 v[240:243], v231, v63, v[240:243]
	s_waitcnt lgkmcnt(1)
	v_mfma_f32_16x16x4_f32 v[200:203], v232, v64, v[200:203]
	s_waitcnt lgkmcnt(1)
	v_mfma_f32_16x16x4_f32 v[240:243], v233, v65, v[240:243]
	s_waitcnt lgkmcnt(1)
	v_mfma_f32_16x16x4_f32 v[200:203], v234, v66, v[200:203]
	s_waitcnt lgkmcnt(1)
	v_mfma_f32_16x16x4_f32 v[240:243], v235, v67, v[240:243]
	s_waitcnt lgkmcnt(0)
	v_mfma_f32_16x16x4_f32 v[200:203], v236, v68, v[200:203]
	s_waitcnt lgkmcnt(0)
	v_mfma_f32_16x16x4_f32 v[240:243], v237, v69, v[240:243]
	s_waitcnt lgkmcnt(0)
	v_mfma_f32_16x16x4_f32 v[200:203], v238, v70, v[200:203]
	s_waitcnt lgkmcnt(0)
; DI unsigned pk2(float a, float b) { f32x2_t v = {a, b}; return __builtin_bit_cast(unsigned, __builtin_convertvector(v, bf16x2_t)); }
; DI float gelu_tanh(float v) { const float z = 0.7978845608028654f * (v + 0.044715f * v * v * v); const float th = 1.0f - 2.0f * __builtin_amdgcn_rcpf(__builtin_amdgcn_exp2f(2.8853900817779268f * z) + 1.0f); return 0.5f * v * (1.0f + th); }
; DI void s5_pass3_item(const Params& P, int bitem, unsigned char* smem) {
;     ...
;         for (int tt = 0; tt < 16; ++tt) { const float bur = xs[lane * 17 + tt], bui = xs[(64 + lane) * 17 + tt];
;             const float nxr = ab[0] * xr - ab[1] * xi + bur, nxi = ab[0] * xi + ab[1] * xr + bui; xr = nxr; xi = nxi;
;             xs[lane * 17 + tt] = xr; xs[(64 + lane) * 17 + tt] = xi; }
;         asm volatile("s_waitcnt lgkmcnt(0)" ::: "memory");
;         f32x4 ya[4];
; #pragma unroll
;         for (int j = 0; j < 4; ++j) ya[j] = (f32x4){0.f, 0.f, 0.f, 0.f};
; #pragma unroll
;         for (int i = 0; i < 32; ++i) { const float a = xs[(4 * i + q) * 17 + r]; ya[i & 3] = __builtin_amdgcn_mfma_f32_16x16x4f32(a, cB[i], ya[i & 3], 0, 0, 0); }
;         const f32x4 y = (ya[0] + ya[1]) + (ya[2] + ya[3]);
; #pragma unroll
;         for (int j = 0; j < 4; ++j) { const int tl = sub * 16 + 4 * q + j; const float v = y[j] + dsk * uv[j];
;             HG[(size_t)(b * TT + ch * 64 + tl) * 1024 + grp * 16 + r] = (bf16_t)(pk2(gelu_tanh(v), 0.f) & 0xffffu); }
	v_mfma_f32_16x16x4_f32 v[240:243], v239, v71, v[240:243]
	s_nop 9
	v_add_f32_e32 v1, v200, v240
	v_add_f32_e32 v2, v201, v241
	v_add_f32_e32 v3, v202, v242
	v_add_f32_e32 v4, v203, v243
	v_fmac_f32_e32 v1, v76, v104
	v_fmac_f32_e32 v2, v76, v105
	v_fmac_f32_e32 v3, v76, v106
	v_fmac_f32_e32 v4, v76, v107
	v_mul_f32_e32 v5, 0x3d372713, v1
	v_mul_f32_e32 v6, 0x3d372713, v2
	v_mul_f32_e32 v7, 0x3d372713, v3
	v_mul_f32_e32 v246, 0x3d372713, v4
	v_mul_f32_e32 v5, v1, v5
	v_mul_f32_e32 v6, v2, v6
	v_mul_f32_e32 v7, v3, v7
	v_mul_f32_e32 v246, v4, v246
	v_mul_f32_e32 v194, 0.5, v1
	v_mul_f32_e32 v195, 0.5, v2
	v_mul_f32_e32 v196, 0.5, v3
	v_mul_f32_e32 v197, 0.5, v4
	v_fma_f32 v1, v1, v5, v1
	v_fma_f32 v2, v2, v6, v2
	v_fma_f32 v3, v3, v7, v3
	v_fma_f32 v4, v4, v246, v4
	v_mul_f32_e32 v1, 0x3f4c422a, v1
	v_mul_f32_e32 v2, 0x3f4c422a, v2
	v_mul_f32_e32 v3, 0x3f4c422a, v3
	v_mul_f32_e32 v4, 0x3f4c422a, v4
	v_mul_f32_e32 v1, 0x4038aa3b, v1
	v_mul_f32_e32 v2, 0x4038aa3b, v2
	v_mul_f32_e32 v3, 0x4038aa3b, v3
	v_mul_f32_e32 v4, 0x4038aa3b, v4
	v_exp_f32_e32 v1, v1
	v_exp_f32_e32 v2, v2
	v_exp_f32_e32 v3, v3
	v_exp_f32_e32 v4, v4
	v_add_f32_e32 v1, 1.0, v1
	v_add_f32_e32 v2, 1.0, v2
	v_add_f32_e32 v3, 1.0, v3
	v_add_f32_e32 v4, 1.0, v4
	v_rcp_f32_e32 v1, v1
	v_rcp_f32_e32 v2, v2
	v_rcp_f32_e32 v3, v3
	v_rcp_f32_e32 v4, v4
	v_fma_f32 v1, v1, -2.0, 1.0
	v_fma_f32 v2, v2, -2.0, 1.0
	v_fma_f32 v3, v3, -2.0, 1.0
	v_fma_f32 v4, v4, -2.0, 1.0
	v_add_f32_e32 v1, 1.0, v1
	v_add_f32_e32 v2, 1.0, v2
	v_add_f32_e32 v3, 1.0, v3
	v_add_f32_e32 v4, 1.0, v4
	v_mul_f32_e32 v1, v194, v1
	v_mul_f32_e32 v2, v195, v2
	v_mul_f32_e32 v3, v196, v3
	v_mul_f32_e32 v4, v197, v4
	v_cvt_pk_bf16_f32 v1, v1, v1
	v_cvt_pk_bf16_f32 v2, v2, v2
	v_cvt_pk_bf16_f32 v3, v3, v3
	v_cvt_pk_bf16_f32 v4, v4, v4
	global_store_short v198, v1, s[28:29] offset:-4096
	global_store_short v198, v2, s[28:29] offset:-2048
	global_store_short v198, v3, s[28:29] offset:0
	global_store_short v198, v4, s[28:29] offset:2048
	s_add_u32 s28, s28, 0x8000
	s_addc_u32 s29, s29, 0
	v_mul_f32_e32 v194, v73, v193
	v_mul_f32_e32 v195, v73, v192
	v_fma_f32 v194, v72, v192, -v194
	v_fma_f32 v195, v72, v193, v195
	v_add_f32_e32 v160, v194, v160
	v_add_f32_e32 v176, v195, v176
	ds_write_addtid_b32 v160 offset:0
	ds_write_addtid_b32 v176 offset:256
	v_mul_f32_e32 v194, v73, v176
	v_mul_f32_e32 v195, v73, v160
	v_fma_f32 v194, v72, v160, -v194
	v_fma_f32 v195, v72, v176, v195
	v_add_f32_e32 v161, v194, v161
	v_add_f32_e32 v177, v195, v177
	ds_write_addtid_b32 v161 offset:528
	ds_write_addtid_b32 v177 offset:784
	v_mul_f32_e32 v194, v73, v177
	v_mul_f32_e32 v195, v73, v161
	v_fma_f32 v194, v72, v161, -v194
	v_fma_f32 v195, v72, v177, v195
	v_add_f32_e32 v162, v194, v162
	v_add_f32_e32 v178, v195, v178
	ds_write_addtid_b32 v162 offset:1056
	ds_write_addtid_b32 v178 offset:1312
	v_mul_f32_e32 v194, v73, v178
	v_mul_f32_e32 v195, v73, v162
	v_fma_f32 v194, v72, v162, -v194
	v_fma_f32 v195, v72, v178, v195
	v_add_f32_e32 v163, v194, v163
	v_add_f32_e32 v179, v195, v179
	ds_write_addtid_b32 v163 offset:1584
	ds_write_addtid_b32 v179 offset:1840
	v_mul_f32_e32 v194, v73, v179
	v_mul_f32_e32 v195, v73, v163
	v_fma_f32 v194, v72, v163, -v194
	v_fma_f32 v195, v72, v179, v195
	v_add_f32_e32 v164, v194, v164
	v_add_f32_e32 v180, v195, v180
	ds_write_addtid_b32 v164 offset:2112
	ds_write_addtid_b32 v180 offset:2368
	v_mul_f32_e32 v194, v73, v180
	v_mul_f32_e32 v195, v73, v164
	v_fma_f32 v194, v72, v164, -v194
	v_fma_f32 v195, v72, v180, v195
	v_add_f32_e32 v165, v194, v165
	v_add_f32_e32 v181, v195, v181
	ds_write_addtid_b32 v165 offset:2640
	ds_write_addtid_b32 v181 offset:2896
	v_mul_f32_e32 v194, v73, v181
	v_mul_f32_e32 v195, v73, v165
	v_fma_f32 v194, v72, v165, -v194
	v_fma_f32 v195, v72, v181, v195
	v_add_f32_e32 v166, v194, v166
	v_add_f32_e32 v182, v195, v182
	ds_write_addtid_b32 v166 offset:3168
	ds_write_addtid_b32 v182 offset:3424
	v_mul_f32_e32 v194, v73, v182
	v_mul_f32_e32 v195, v73, v166
	v_fma_f32 v194, v72, v166, -v194
	v_fma_f32 v195, v72, v182, v195
	v_add_f32_e32 v167, v194, v167
	v_add_f32_e32 v183, v195, v183
	ds_write_addtid_b32 v167 offset:3696
	ds_write_addtid_b32 v183 offset:3952
	v_mul_f32_e32 v194, v73, v183
	v_mul_f32_e32 v195, v73, v167
	v_fma_f32 v194, v72, v167, -v194
	v_fma_f32 v195, v72, v183, v195
	v_add_f32_e32 v168, v194, v168
	v_add_f32_e32 v184, v195, v184
	ds_write_addtid_b32 v168 offset:4224
	ds_write_addtid_b32 v184 offset:4480
	v_mul_f32_e32 v194, v73, v184
	v_mul_f32_e32 v195, v73, v168
	v_fma_f32 v194, v72, v168, -v194
	v_fma_f32 v195, v72, v184, v195
	v_add_f32_e32 v169, v194, v169
	v_add_f32_e32 v185, v195, v185
	ds_write_addtid_b32 v169 offset:4752
	ds_write_addtid_b32 v185 offset:5008
	v_mul_f32_e32 v194, v73, v185
	v_mul_f32_e32 v195, v73, v169
	v_fma_f32 v194, v72, v169, -v194
	v_fma_f32 v195, v72, v185, v195
	v_add_f32_e32 v170, v194, v170
	v_add_f32_e32 v186, v195, v186
	ds_write_addtid_b32 v170 offset:5280
	ds_write_addtid_b32 v186 offset:5536
	v_mul_f32_e32 v194, v73, v186
	v_mul_f32_e32 v195, v73, v170
	v_fma_f32 v194, v72, v170, -v194
	v_fma_f32 v195, v72, v186, v195
	v_add_f32_e32 v171, v194, v171
	v_add_f32_e32 v187, v195, v187
	ds_write_addtid_b32 v171 offset:5808
	ds_write_addtid_b32 v187 offset:6064
	v_mul_f32_e32 v194, v73, v187
	v_mul_f32_e32 v195, v73, v171
	v_fma_f32 v194, v72, v171, -v194
	v_fma_f32 v195, v72, v187, v195
	v_add_f32_e32 v172, v194, v172
	v_add_f32_e32 v188, v195, v188
	ds_write_addtid_b32 v172 offset:6336
	ds_write_addtid_b32 v188 offset:6592
	v_mul_f32_e32 v194, v73, v188
	v_mul_f32_e32 v195, v73, v172
	v_fma_f32 v194, v72, v172, -v194
; DI void s5_pass3_item(const Params& P, int bitem, unsigned char* smem) {
;     ...
;         for (int tt = 0; tt < 16; ++tt) { const float bur = xs[lane * 17 + tt], bui = xs[(64 + lane) * 17 + tt];
;             const float nxr = ab[0] * xr - ab[1] * xi + bur, nxi = ab[0] * xi + ab[1] * xr + bui; xr = nxr; xi = nxi;
;             xs[lane * 17 + tt] = xr; xs[(64 + lane) * 17 + tt] = xi; }
;         asm volatile("s_waitcnt lgkmcnt(0)" ::: "memory");
;         f32x4 ya[4];
; #pragma unroll
;         for (int j = 0; j < 4; ++j) ya[j] = (f32x4){0.f, 0.f, 0.f, 0.f};
; #pragma unroll
;         for (int i = 0; i < 32; ++i) { const float a = xs[(4 * i + q) * 17 + r]; ya[i & 3] = __builtin_amdgcn_mfma_f32_16x16x4f32(a, cB[i], ya[i & 3], 0, 0, 0); }
	v_fma_f32 v195, v72, v188, v195
	v_add_f32_e32 v173, v194, v173
	v_add_f32_e32 v189, v195, v189
	ds_write_addtid_b32 v173 offset:6864
	ds_write_addtid_b32 v189 offset:7120
	v_mul_f32_e32 v194, v73, v189
	v_mul_f32_e32 v195, v73, v173
	v_fma_f32 v194, v72, v173, -v194
	v_fma_f32 v195, v72, v189, v195
	v_add_f32_e32 v174, v194, v174
	v_add_f32_e32 v190, v195, v190
	ds_write_addtid_b32 v174 offset:7392
	ds_write_addtid_b32 v190 offset:7648
	v_mul_f32_e32 v194, v73, v190
	v_mul_f32_e32 v195, v73, v174
	v_fma_f32 v194, v72, v174, -v194
	v_fma_f32 v195, v72, v190, v195
	v_add_f32_e32 v175, v194, v175
	v_add_f32_e32 v191, v195, v191
	ds_write_addtid_b32 v175 offset:7920
	ds_write_addtid_b32 v191 offset:8176
	v_mov_b32_e32 v192, v175
	v_mov_b32_e32 v193, v191
	ds_read_b128 v[208:211], v77 offset:0
	ds_read_b128 v[212:215], v77 offset:64
	ds_read_b128 v[216:219], v77 offset:128
	ds_read_b128 v[220:223], v77 offset:192
	ds_read_b128 v[224:227], v77 offset:256
	ds_read_b128 v[228:231], v77 offset:320
	ds_read_b128 v[232:235], v77 offset:384
	ds_read_b128 v[236:239], v77 offset:448
	v_mfma_f32_16x16x32_bf16 v[160:163], v[96:99], v[8:11], 0
	v_mfma_f32_16x16x32_bf16 v[164:167], v[96:99], v[12:15], 0
	v_mfma_f32_16x16x32_bf16 v[168:171], v[96:99], v[16:19], 0
	v_mfma_f32_16x16x32_bf16 v[172:175], v[96:99], v[20:23], 0
	v_mfma_f32_16x16x32_bf16 v[176:179], v[96:99], v[24:27], 0
	v_mfma_f32_16x16x32_bf16 v[180:183], v[96:99], v[28:31], 0
	v_mfma_f32_16x16x32_bf16 v[184:187], v[96:99], v[32:35], 0
	v_mfma_f32_16x16x32_bf16 v[188:191], v[96:99], v[36:39], 0
	s_nop 7
	v_permlane32_swap_b32_e32 v160, v168
	v_permlane32_swap_b32_e32 v161, v169
	v_permlane32_swap_b32_e32 v162, v170
	v_permlane32_swap_b32_e32 v163, v171
	v_permlane32_swap_b32_e32 v164, v172
	v_permlane32_swap_b32_e32 v165, v173
	v_permlane32_swap_b32_e32 v166, v174
	v_permlane32_swap_b32_e32 v167, v175
	v_permlane32_swap_b32_e32 v176, v184
	v_permlane32_swap_b32_e32 v177, v185
	v_permlane32_swap_b32_e32 v178, v186
	v_permlane32_swap_b32_e32 v179, v187
	v_permlane32_swap_b32_e32 v180, v188
	v_permlane32_swap_b32_e32 v181, v189
	v_permlane32_swap_b32_e32 v182, v190
	v_permlane32_swap_b32_e32 v183, v191
	v_permlane16_swap_b32_e32 v160, v164
	v_permlane16_swap_b32_e32 v161, v165
	v_permlane16_swap_b32_e32 v162, v166
	v_permlane16_swap_b32_e32 v163, v167
	v_permlane16_swap_b32_e32 v168, v172
	v_permlane16_swap_b32_e32 v169, v173
	v_permlane16_swap_b32_e32 v170, v174
	v_permlane16_swap_b32_e32 v171, v175
	v_permlane16_swap_b32_e32 v176, v180
	v_permlane16_swap_b32_e32 v177, v181
	v_permlane16_swap_b32_e32 v178, v182
	v_permlane16_swap_b32_e32 v179, v183
	v_permlane16_swap_b32_e32 v184, v188
	v_permlane16_swap_b32_e32 v185, v189
	v_permlane16_swap_b32_e32 v186, v190
	v_permlane16_swap_b32_e32 v187, v191
	s_waitcnt lgkmcnt(7)
	v_mfma_f32_16x16x4_f32 v[200:203], v208, v40, 0
	s_waitcnt lgkmcnt(7)
	v_mfma_f32_16x16x4_f32 v[240:243], v209, v41, 0
	s_waitcnt lgkmcnt(7)
	v_mfma_f32_16x16x4_f32 v[200:203], v210, v42, v[200:203]
	s_waitcnt lgkmcnt(7)
	v_mfma_f32_16x16x4_f32 v[240:243], v211, v43, v[240:243]
	s_waitcnt lgkmcnt(6)
	v_mfma_f32_16x16x4_f32 v[200:203], v212, v44, v[200:203]
	s_waitcnt lgkmcnt(6)
	v_mfma_f32_16x16x4_f32 v[240:243], v213, v45, v[240:243]
	s_waitcnt lgkmcnt(6)
	v_mfma_f32_16x16x4_f32 v[200:203], v214, v46, v[200:203]
	s_waitcnt lgkmcnt(6)
	v_mfma_f32_16x16x4_f32 v[240:243], v215, v47, v[240:243]
	s_waitcnt lgkmcnt(5)
	v_mfma_f32_16x16x4_f32 v[200:203], v216, v48, v[200:203]
	s_waitcnt lgkmcnt(5)
	v_mfma_f32_16x16x4_f32 v[240:243], v217, v49, v[240:243]
	s_waitcnt lgkmcnt(5)
	v_mfma_f32_16x16x4_f32 v[200:203], v218, v50, v[200:203]
	s_waitcnt lgkmcnt(5)
	v_mfma_f32_16x16x4_f32 v[240:243], v219, v51, v[240:243]
	s_waitcnt lgkmcnt(4)
	v_mfma_f32_16x16x4_f32 v[200:203], v220, v52, v[200:203]
	s_waitcnt lgkmcnt(4)
	v_mfma_f32_16x16x4_f32 v[240:243], v221, v53, v[240:243]
	s_waitcnt lgkmcnt(4)
	v_mfma_f32_16x16x4_f32 v[200:203], v222, v54, v[200:203]
	s_waitcnt lgkmcnt(4)
	v_mfma_f32_16x16x4_f32 v[240:243], v223, v55, v[240:243]
	s_waitcnt lgkmcnt(3)
	v_mfma_f32_16x16x4_f32 v[200:203], v224, v56, v[200:203]
	s_waitcnt lgkmcnt(3)
	v_mfma_f32_16x16x4_f32 v[240:243], v225, v57, v[240:243]
	s_waitcnt lgkmcnt(3)
	v_mfma_f32_16x16x4_f32 v[200:203], v226, v58, v[200:203]
	s_waitcnt lgkmcnt(3)
	v_mfma_f32_16x16x4_f32 v[240:243], v227, v59, v[240:243]
	s_waitcnt lgkmcnt(2)
	v_mfma_f32_16x16x4_f32 v[200:203], v228, v60, v[200:203]
	s_waitcnt lgkmcnt(2)
	v_mfma_f32_16x16x4_f32 v[240:243], v229, v61, v[240:243]
	s_waitcnt lgkmcnt(2)
	v_mfma_f32_16x16x4_f32 v[200:203], v230, v62, v[200:203]
	s_waitcnt lgkmcnt(2)
	v_mfma_f32_16x16x4_f32 v[240:243], v231, v63, v[240:243]
	s_waitcnt lgkmcnt(1)
	v_mfma_f32_16x16x4_f32 v[200:203], v232, v64, v[200:203]
	s_waitcnt lgkmcnt(1)
	v_mfma_f32_16x16x4_f32 v[240:243], v233, v65, v[240:243]
	s_waitcnt lgkmcnt(1)
	v_mfma_f32_16x16x4_f32 v[200:203], v234, v66, v[200:203]
	s_waitcnt lgkmcnt(1)
	v_mfma_f32_16x16x4_f32 v[240:243], v235, v67, v[240:243]
	s_waitcnt lgkmcnt(0)
	v_mfma_f32_16x16x4_f32 v[200:203], v236, v68, v[200:203]
	s_waitcnt lgkmcnt(0)
	v_mfma_f32_16x16x4_f32 v[240:243], v237, v69, v[240:243]
	s_waitcnt lgkmcnt(0)
	v_mfma_f32_16x16x4_f32 v[200:203], v238, v70, v[200:203]
	s_waitcnt lgkmcnt(0)
; DI unsigned pk2(float a, float b) { f32x2_t v = {a, b}; return __builtin_bit_cast(unsigned, __builtin_convertvector(v, bf16x2_t)); }
; DI float gelu_tanh(float v) { const float z = 0.7978845608028654f * (v + 0.044715f * v * v * v); const float th = 1.0f - 2.0f * __builtin_amdgcn_rcpf(__builtin_amdgcn_exp2f(2.8853900817779268f * z) + 1.0f); return 0.5f * v * (1.0f + th); }
; DI void s5_pass3_item(const Params& P, int bitem, unsigned char* smem) {
;     ...
;       const f32x2_t* e = (const f32x2_t*)(ws + WS_S5END) + (size_t)((b * 64 + grp) * 32) * 64 + lane;
;       f32x2_t ev[31];
; #pragma unroll
;       for (int j = 0; j < 31; ++j) ev[j] = e[(j < ch ? j : 0) * 64];
;     ...
;         for (int i = 0; i < 32; ++i) { const float a = xs[(4 * i + q) * 17 + r]; ya[i & 3] = __builtin_amdgcn_mfma_f32_16x16x4f32(a, cB[i], ya[i & 3], 0, 0, 0); }
;         const f32x4 y = (ya[0] + ya[1]) + (ya[2] + ya[3]);
; #pragma unroll
;         for (int j = 0; j < 4; ++j) { const int tl = sub * 16 + 4 * q + j; const float v = y[j] + dsk * uv[j];
;             HG[(size_t)(b * TT + ch * 64 + tl) * 1024 + grp * 16 + r] = (bf16_t)(pk2(gelu_tanh(v), 0.f) & 0xffffu); }
	v_mfma_f32_16x16x4_f32 v[240:243], v239, v71, v[240:243]
	s_nop 9
	v_add_f32_e32 v1, v200, v240
	v_add_f32_e32 v2, v201, v241
	v_add_f32_e32 v3, v202, v242
	v_add_f32_e32 v4, v203, v243
	v_fmac_f32_e32 v1, v76, v108
	v_fmac_f32_e32 v2, v76, v109
	v_fmac_f32_e32 v3, v76, v110
	v_fmac_f32_e32 v4, v76, v111
	v_mul_f32_e32 v5, 0x3d372713, v1
	v_mul_f32_e32 v6, 0x3d372713, v2
	v_mul_f32_e32 v7, 0x3d372713, v3
	v_mul_f32_e32 v246, 0x3d372713, v4
	v_mul_f32_e32 v5, v1, v5
	v_mul_f32_e32 v6, v2, v6
	v_mul_f32_e32 v7, v3, v7
	v_mul_f32_e32 v246, v4, v246
	v_mul_f32_e32 v194, 0.5, v1
	v_mul_f32_e32 v195, 0.5, v2
	v_mul_f32_e32 v196, 0.5, v3
	v_mul_f32_e32 v197, 0.5, v4
	v_fma_f32 v1, v1, v5, v1
	v_fma_f32 v2, v2, v6, v2
	v_fma_f32 v3, v3, v7, v3
	v_fma_f32 v4, v4, v246, v4
	v_mul_f32_e32 v1, 0x3f4c422a, v1
	v_mul_f32_e32 v2, 0x3f4c422a, v2
	v_mul_f32_e32 v3, 0x3f4c422a, v3
	v_mul_f32_e32 v4, 0x3f4c422a, v4
	v_mul_f32_e32 v1, 0x4038aa3b, v1
	v_mul_f32_e32 v2, 0x4038aa3b, v2
	v_mul_f32_e32 v3, 0x4038aa3b, v3
	v_mul_f32_e32 v4, 0x4038aa3b, v4
	v_exp_f32_e32 v1, v1
	v_exp_f32_e32 v2, v2
	v_exp_f32_e32 v3, v3
	v_exp_f32_e32 v4, v4
	v_add_f32_e32 v1, 1.0, v1
	v_add_f32_e32 v2, 1.0, v2
	v_add_f32_e32 v3, 1.0, v3
	v_add_f32_e32 v4, 1.0, v4
	v_rcp_f32_e32 v1, v1
	v_rcp_f32_e32 v2, v2
	v_rcp_f32_e32 v3, v3
	v_rcp_f32_e32 v4, v4
	v_fma_f32 v1, v1, -2.0, 1.0
	v_fma_f32 v2, v2, -2.0, 1.0
	v_fma_f32 v3, v3, -2.0, 1.0
	v_fma_f32 v4, v4, -2.0, 1.0
	v_add_f32_e32 v1, 1.0, v1
	v_add_f32_e32 v2, 1.0, v2
	v_add_f32_e32 v3, 1.0, v3
	v_add_f32_e32 v4, 1.0, v4
	v_mul_f32_e32 v1, v194, v1
	v_mul_f32_e32 v2, v195, v2
	v_mul_f32_e32 v3, v196, v3
	v_mul_f32_e32 v4, v197, v4
	v_cvt_pk_bf16_f32 v1, v1, v1
	v_cvt_pk_bf16_f32 v2, v2, v2
	v_cvt_pk_bf16_f32 v3, v3, v3
	v_cvt_pk_bf16_f32 v4, v4, v4
	global_store_short v198, v1, s[28:29] offset:-4096
	global_store_short v198, v2, s[28:29] offset:-2048
	global_store_short v198, v3, s[28:29] offset:0
	global_store_short v198, v4, s[28:29] offset:2048
	s_add_u32 s28, s28, 0x8000
	s_addc_u32 s29, s29, 0
	s_cmp_eq_u32 s19, 7
	s_cbranch_scc1 .Ls5n_nostage
	s_waitcnt vmcnt(8)
	s_xor_b32 s0, s20, 0x4000
	v_add_u32_e32 v1, s0, v81
	ds_write_b64 v1, v[152:153] offset:0
	ds_write_b64 v1, v[154:155] offset:4096
	ds_write_b64 v1, v[156:157] offset:8192
	ds_write_b64 v1, v[158:159] offset:12288
	s_add_i32 s0, s19, 2
	v_mov_b32_e32 v2, s0
	s_waitcnt lgkmcnt(0)
	ds_write_b32 v78, v2
.Ls5n_nostage:
	v_mul_f32_e32 v194, v73, v193
	v_mul_f32_e32 v195, v73, v192
	v_fma_f32 v194, v72, v192, -v194
	v_fma_f32 v195, v72, v193, v195
	v_add_f32_e32 v160, v194, v160
	v_add_f32_e32 v176, v195, v176
	ds_write_addtid_b32 v160 offset:0
	ds_write_addtid_b32 v176 offset:256
	v_mul_f32_e32 v194, v73, v176
	v_mul_f32_e32 v195, v73, v160
	v_fma_f32 v194, v72, v160, -v194
	v_fma_f32 v195, v72, v176, v195
	v_add_f32_e32 v161, v194, v161
	v_add_f32_e32 v177, v195, v177
	ds_write_addtid_b32 v161 offset:528
	ds_write_addtid_b32 v177 offset:784
	v_mul_f32_e32 v194, v73, v177
	v_mul_f32_e32 v195, v73, v161
	v_fma_f32 v194, v72, v161, -v194
	v_fma_f32 v195, v72, v177, v195
	v_add_f32_e32 v162, v194, v162
	v_add_f32_e32 v178, v195, v178
	ds_write_addtid_b32 v162 offset:1056
	ds_write_addtid_b32 v178 offset:1312
	v_mul_f32_e32 v194, v73, v178
	v_mul_f32_e32 v195, v73, v162
	v_fma_f32 v194, v72, v162, -v194
	v_fma_f32 v195, v72, v178, v195
	v_add_f32_e32 v163, v194, v163
	v_add_f32_e32 v179, v195, v179
	ds_write_addtid_b32 v163 offset:1584
	ds_write_addtid_b32 v179 offset:1840
	v_mul_f32_e32 v194, v73, v179
	v_mul_f32_e32 v195, v73, v163
	v_fma_f32 v194, v72, v163, -v194
	v_fma_f32 v195, v72, v179, v195
	v_add_f32_e32 v164, v194, v164
	v_add_f32_e32 v180, v195, v180
	ds_write_addtid_b32 v164 offset:2112
	ds_write_addtid_b32 v180 offset:2368
	v_mul_f32_e32 v194, v73, v180
	v_mul_f32_e32 v195, v73, v164
	v_fma_f32 v194, v72, v164, -v194
	v_fma_f32 v195, v72, v180, v195
	v_add_f32_e32 v165, v194, v165
	v_add_f32_e32 v181, v195, v181
	ds_write_addtid_b32 v165 offset:2640
	ds_write_addtid_b32 v181 offset:2896
	v_mul_f32_e32 v194, v73, v181
	v_mul_f32_e32 v195, v73, v165
	v_fma_f32 v194, v72, v165, -v194
	v_fma_f32 v195, v72, v181, v195
	v_add_f32_e32 v166, v194, v166
	v_add_f32_e32 v182, v195, v182
	ds_write_addtid_b32 v166 offset:3168
	ds_write_addtid_b32 v182 offset:3424
	v_mul_f32_e32 v194, v73, v182
	v_mul_f32_e32 v195, v73, v166
	v_fma_f32 v194, v72, v166, -v194
	v_fma_f32 v195, v72, v182, v195
	v_add_f32_e32 v167, v194, v167
	v_add_f32_e32 v183, v195, v183
	ds_write_addtid_b32 v167 offset:3696
	ds_write_addtid_b32 v183 offset:3952
	v_mul_f32_e32 v194, v73, v183
	v_mul_f32_e32 v195, v73, v167
	v_fma_f32 v194, v72, v167, -v194
	v_fma_f32 v195, v72, v183, v195
	v_add_f32_e32 v168, v194, v168
	v_add_f32_e32 v184, v195, v184
	ds_write_addtid_b32 v168 offset:4224
	ds_write_addtid_b32 v184 offset:4480
	v_mul_f32_e32 v194, v73, v184
	v_mul_f32_e32 v195, v73, v168
	v_fma_f32 v194, v72, v168, -v194
	v_fma_f32 v195, v72, v184, v195
	v_add_f32_e32 v169, v194, v169
	v_add_f32_e32 v185, v195, v185
	ds_write_addtid_b32 v169 offset:4752
	ds_write_addtid_b32 v185 offset:5008
	v_mul_f32_e32 v194, v73, v185
	v_mul_f32_e32 v195, v73, v169
	v_fma_f32 v194, v72, v169, -v194
	v_fma_f32 v195, v72, v185, v195
	v_add_f32_e32 v170, v194, v170
	v_add_f32_e32 v186, v195, v186
	ds_write_addtid_b32 v170 offset:5280
	ds_write_addtid_b32 v186 offset:5536
	v_mul_f32_e32 v194, v73, v186
	v_mul_f32_e32 v195, v73, v170
	v_fma_f32 v194, v72, v170, -v194
	v_fma_f32 v195, v72, v186, v195
	v_add_f32_e32 v171, v194, v171
	v_add_f32_e32 v187, v195, v187
	ds_write_addtid_b32 v171 offset:5808
	ds_write_addtid_b32 v187 offset:6064
; DI void s5_pass3_item(const Params& P, int bitem, unsigned char* smem) {
;     ...
;         for (int tt = 0; tt < 16; ++tt) { const float bur = xs[lane * 17 + tt], bui = xs[(64 + lane) * 17 + tt];
;             const float nxr = ab[0] * xr - ab[1] * xi + bur, nxi = ab[0] * xi + ab[1] * xr + bui; xr = nxr; xi = nxi;
;             xs[lane * 17 + tt] = xr; xs[(64 + lane) * 17 + tt] = xi; }
;         asm volatile("s_waitcnt lgkmcnt(0)" ::: "memory");
;         f32x4 ya[4];
; #pragma unroll
;         for (int j = 0; j < 4; ++j) ya[j] = (f32x4){0.f, 0.f, 0.f, 0.f};
; #pragma unroll
;         for (int i = 0; i < 32; ++i) { const float a = xs[(4 * i + q) * 17 + r]; ya[i & 3] = __builtin_amdgcn_mfma_f32_16x16x4f32(a, cB[i], ya[i & 3], 0, 0, 0); }
	v_mul_f32_e32 v194, v73, v187
	v_mul_f32_e32 v195, v73, v171
	v_fma_f32 v194, v72, v171, -v194
	v_fma_f32 v195, v72, v187, v195
	v_add_f32_e32 v172, v194, v172
	v_add_f32_e32 v188, v195, v188
	ds_write_addtid_b32 v172 offset:6336
	ds_write_addtid_b32 v188 offset:6592
	v_mul_f32_e32 v194, v73, v188
	v_mul_f32_e32 v195, v73, v172
	v_fma_f32 v194, v72, v172, -v194
	v_fma_f32 v195, v72, v188, v195
	v_add_f32_e32 v173, v194, v173
	v_add_f32_e32 v189, v195, v189
	ds_write_addtid_b32 v173 offset:6864
	ds_write_addtid_b32 v189 offset:7120
	v_mul_f32_e32 v194, v73, v189
	v_mul_f32_e32 v195, v73, v173
	v_fma_f32 v194, v72, v173, -v194
	v_fma_f32 v195, v72, v189, v195
	v_add_f32_e32 v174, v194, v174
	v_add_f32_e32 v190, v195, v190
	ds_write_addtid_b32 v174 offset:7392
	ds_write_addtid_b32 v190 offset:7648
	v_mul_f32_e32 v194, v73, v190
	v_mul_f32_e32 v195, v73, v174
	v_fma_f32 v194, v72, v174, -v194
	v_fma_f32 v195, v72, v190, v195
	v_add_f32_e32 v175, v194, v175
	v_add_f32_e32 v191, v195, v191
	ds_write_addtid_b32 v175 offset:7920
	ds_write_addtid_b32 v191 offset:8176
	v_mov_b32_e32 v192, v175
	v_mov_b32_e32 v193, v191
	ds_read_b128 v[208:211], v77 offset:0
	ds_read_b128 v[212:215], v77 offset:64
	ds_read_b128 v[216:219], v77 offset:128
	ds_read_b128 v[220:223], v77 offset:192
	ds_read_b128 v[224:227], v77 offset:256
	ds_read_b128 v[228:231], v77 offset:320
	ds_read_b128 v[232:235], v77 offset:384
	ds_read_b128 v[236:239], v77 offset:448
	v_mfma_f32_16x16x32_bf16 v[160:163], v[100:103], v[8:11], 0
	v_mfma_f32_16x16x32_bf16 v[164:167], v[100:103], v[12:15], 0
	v_mfma_f32_16x16x32_bf16 v[168:171], v[100:103], v[16:19], 0
	v_mfma_f32_16x16x32_bf16 v[172:175], v[100:103], v[20:23], 0
	v_mfma_f32_16x16x32_bf16 v[176:179], v[100:103], v[24:27], 0
	v_mfma_f32_16x16x32_bf16 v[180:183], v[100:103], v[28:31], 0
	v_mfma_f32_16x16x32_bf16 v[184:187], v[100:103], v[32:35], 0
	v_mfma_f32_16x16x32_bf16 v[188:191], v[100:103], v[36:39], 0
	s_nop 7
	v_permlane32_swap_b32_e32 v160, v168
	v_permlane32_swap_b32_e32 v161, v169
	v_permlane32_swap_b32_e32 v162, v170
	v_permlane32_swap_b32_e32 v163, v171
	v_permlane32_swap_b32_e32 v164, v172
	v_permlane32_swap_b32_e32 v165, v173
	v_permlane32_swap_b32_e32 v166, v174
	v_permlane32_swap_b32_e32 v167, v175
	v_permlane32_swap_b32_e32 v176, v184
	v_permlane32_swap_b32_e32 v177, v185
	v_permlane32_swap_b32_e32 v178, v186
	v_permlane32_swap_b32_e32 v179, v187
	v_permlane32_swap_b32_e32 v180, v188
	v_permlane32_swap_b32_e32 v181, v189
	v_permlane32_swap_b32_e32 v182, v190
	v_permlane32_swap_b32_e32 v183, v191
	v_permlane16_swap_b32_e32 v160, v164
	v_permlane16_swap_b32_e32 v161, v165
	v_permlane16_swap_b32_e32 v162, v166
	v_permlane16_swap_b32_e32 v163, v167
	v_permlane16_swap_b32_e32 v168, v172
	v_permlane16_swap_b32_e32 v169, v173
	v_permlane16_swap_b32_e32 v170, v174
	v_permlane16_swap_b32_e32 v171, v175
	v_permlane16_swap_b32_e32 v176, v180
	v_permlane16_swap_b32_e32 v177, v181
	v_permlane16_swap_b32_e32 v178, v182
	v_permlane16_swap_b32_e32 v179, v183
	v_permlane16_swap_b32_e32 v184, v188
	v_permlane16_swap_b32_e32 v185, v189
	v_permlane16_swap_b32_e32 v186, v190
	v_permlane16_swap_b32_e32 v187, v191
	s_waitcnt lgkmcnt(7)
	v_mfma_f32_16x16x4_f32 v[200:203], v208, v40, 0
	s_waitcnt lgkmcnt(7)
	v_mfma_f32_16x16x4_f32 v[240:243], v209, v41, 0
	s_waitcnt lgkmcnt(7)
	v_mfma_f32_16x16x4_f32 v[200:203], v210, v42, v[200:203]
	s_waitcnt lgkmcnt(7)
	v_mfma_f32_16x16x4_f32 v[240:243], v211, v43, v[240:243]
	s_waitcnt lgkmcnt(6)
	v_mfma_f32_16x16x4_f32 v[200:203], v212, v44, v[200:203]
	s_waitcnt lgkmcnt(6)
	v_mfma_f32_16x16x4_f32 v[240:243], v213, v45, v[240:243]
	s_waitcnt lgkmcnt(6)
	v_mfma_f32_16x16x4_f32 v[200:203], v214, v46, v[200:203]
	s_waitcnt lgkmcnt(6)
	v_mfma_f32_16x16x4_f32 v[240:243], v215, v47, v[240:243]
	s_waitcnt lgkmcnt(5)
	v_mfma_f32_16x16x4_f32 v[200:203], v216, v48, v[200:203]
	s_waitcnt lgkmcnt(5)
	v_mfma_f32_16x16x4_f32 v[240:243], v217, v49, v[240:243]
	s_waitcnt lgkmcnt(5)
	v_mfma_f32_16x16x4_f32 v[200:203], v218, v50, v[200:203]
	s_waitcnt lgkmcnt(5)
	v_mfma_f32_16x16x4_f32 v[240:243], v219, v51, v[240:243]
	s_waitcnt lgkmcnt(4)
	v_mfma_f32_16x16x4_f32 v[200:203], v220, v52, v[200:203]
	s_waitcnt lgkmcnt(4)
	v_mfma_f32_16x16x4_f32 v[240:243], v221, v53, v[240:243]
	s_waitcnt lgkmcnt(4)
	v_mfma_f32_16x16x4_f32 v[200:203], v222, v54, v[200:203]
	s_waitcnt lgkmcnt(4)
	v_mfma_f32_16x16x4_f32 v[240:243], v223, v55, v[240:243]
	s_waitcnt lgkmcnt(3)
	v_mfma_f32_16x16x4_f32 v[200:203], v224, v56, v[200:203]
	s_waitcnt lgkmcnt(3)
	v_mfma_f32_16x16x4_f32 v[240:243], v225, v57, v[240:243]
	s_waitcnt lgkmcnt(3)
	v_mfma_f32_16x16x4_f32 v[200:203], v226, v58, v[200:203]
	s_waitcnt lgkmcnt(3)
	v_mfma_f32_16x16x4_f32 v[240:243], v227, v59, v[240:243]
	s_waitcnt lgkmcnt(2)
	v_mfma_f32_16x16x4_f32 v[200:203], v228, v60, v[200:203]
	s_waitcnt lgkmcnt(2)
	v_mfma_f32_16x16x4_f32 v[240:243], v229, v61, v[240:243]
	s_waitcnt lgkmcnt(2)
	v_mfma_f32_16x16x4_f32 v[200:203], v230, v62, v[200:203]
	s_waitcnt lgkmcnt(2)
	v_mfma_f32_16x16x4_f32 v[240:243], v231, v63, v[240:243]
	s_waitcnt lgkmcnt(1)
	v_mfma_f32_16x16x4_f32 v[200:203], v232, v64, v[200:203]
	s_waitcnt lgkmcnt(1)
	v_mfma_f32_16x16x4_f32 v[240:243], v233, v65, v[240:243]
	s_waitcnt lgkmcnt(1)
	v_mfma_f32_16x16x4_f32 v[200:203], v234, v66, v[200:203]
	s_waitcnt lgkmcnt(1)
	v_mfma_f32_16x16x4_f32 v[240:243], v235, v67, v[240:243]
	s_waitcnt lgkmcnt(0)
	v_mfma_f32_16x16x4_f32 v[200:203], v236, v68, v[200:203]
	s_waitcnt lgkmcnt(0)
	v_mfma_f32_16x16x4_f32 v[240:243], v237, v69, v[240:243]
	s_waitcnt lgkmcnt(0)
	v_mfma_f32_16x16x4_f32 v[200:203], v238, v70, v[200:203]
	s_waitcnt lgkmcnt(0)
; DI unsigned pk2(float a, float b) { f32x2_t v = {a, b}; return __builtin_bit_cast(unsigned, __builtin_convertvector(v, bf16x2_t)); }
; DI float gelu_tanh(float v) { const float z = 0.7978845608028654f * (v + 0.044715f * v * v * v); const float th = 1.0f - 2.0f * __builtin_amdgcn_rcpf(__builtin_amdgcn_exp2f(2.8853900817779268f * z) + 1.0f); return 0.5f * v * (1.0f + th); }
; DI void s5_pass3_item(const Params& P, int bitem, unsigned char* smem) {
;     ...
;         for (int tt = 0; tt < 16; ++tt) { const float bur = xs[lane * 17 + tt], bui = xs[(64 + lane) * 17 + tt];
;             const float nxr = ab[0] * xr - ab[1] * xi + bur, nxi = ab[0] * xi + ab[1] * xr + bui; xr = nxr; xi = nxi;
;             xs[lane * 17 + tt] = xr; xs[(64 + lane) * 17 + tt] = xi; }
;         asm volatile("s_waitcnt lgkmcnt(0)" ::: "memory");
;         f32x4 ya[4];
; #pragma unroll
;         for (int j = 0; j < 4; ++j) ya[j] = (f32x4){0.f, 0.f, 0.f, 0.f};
; #pragma unroll
;         for (int i = 0; i < 32; ++i) { const float a = xs[(4 * i + q) * 17 + r]; ya[i & 3] = __builtin_amdgcn_mfma_f32_16x16x4f32(a, cB[i], ya[i & 3], 0, 0, 0); }
;         const f32x4 y = (ya[0] + ya[1]) + (ya[2] + ya[3]);
; #pragma unroll
;         for (int j = 0; j < 4; ++j) { const int tl = sub * 16 + 4 * q + j; const float v = y[j] + dsk * uv[j];
;             HG[(size_t)(b * TT + ch * 64 + tl) * 1024 + grp * 16 + r] = (bf16_t)(pk2(gelu_tanh(v), 0.f) & 0xffffu); }
	v_mfma_f32_16x16x4_f32 v[240:243], v239, v71, v[240:243]
	s_nop 9
	v_add_f32_e32 v1, v200, v240
	v_add_f32_e32 v2, v201, v241
	v_add_f32_e32 v3, v202, v242
	v_add_f32_e32 v4, v203, v243
	v_fmac_f32_e32 v1, v76, v112
	v_fmac_f32_e32 v2, v76, v113
	v_fmac_f32_e32 v3, v76, v114
	v_fmac_f32_e32 v4, v76, v115
	v_mul_f32_e32 v5, 0x3d372713, v1
	v_mul_f32_e32 v6, 0x3d372713, v2
	v_mul_f32_e32 v7, 0x3d372713, v3
	v_mul_f32_e32 v246, 0x3d372713, v4
	v_mul_f32_e32 v5, v1, v5
	v_mul_f32_e32 v6, v2, v6
	v_mul_f32_e32 v7, v3, v7
	v_mul_f32_e32 v246, v4, v246
	v_mul_f32_e32 v194, 0.5, v1
	v_mul_f32_e32 v195, 0.5, v2
	v_mul_f32_e32 v196, 0.5, v3
	v_mul_f32_e32 v197, 0.5, v4
	v_fma_f32 v1, v1, v5, v1
	v_fma_f32 v2, v2, v6, v2
	v_fma_f32 v3, v3, v7, v3
	v_fma_f32 v4, v4, v246, v4
	v_mul_f32_e32 v1, 0x3f4c422a, v1
	v_mul_f32_e32 v2, 0x3f4c422a, v2
	v_mul_f32_e32 v3, 0x3f4c422a, v3
	v_mul_f32_e32 v4, 0x3f4c422a, v4
	v_mul_f32_e32 v1, 0x4038aa3b, v1
	v_mul_f32_e32 v2, 0x4038aa3b, v2
	v_mul_f32_e32 v3, 0x4038aa3b, v3
	v_mul_f32_e32 v4, 0x4038aa3b, v4
	v_exp_f32_e32 v1, v1
	v_exp_f32_e32 v2, v2
	v_exp_f32_e32 v3, v3
	v_exp_f32_e32 v4, v4
	v_add_f32_e32 v1, 1.0, v1
	v_add_f32_e32 v2, 1.0, v2
	v_add_f32_e32 v3, 1.0, v3
	v_add_f32_e32 v4, 1.0, v4
	v_rcp_f32_e32 v1, v1
	v_rcp_f32_e32 v2, v2
	v_rcp_f32_e32 v3, v3
	v_rcp_f32_e32 v4, v4
	v_fma_f32 v1, v1, -2.0, 1.0
	v_fma_f32 v2, v2, -2.0, 1.0
	v_fma_f32 v3, v3, -2.0, 1.0
	v_fma_f32 v4, v4, -2.0, 1.0
	v_add_f32_e32 v1, 1.0, v1
	v_add_f32_e32 v2, 1.0, v2
	v_add_f32_e32 v3, 1.0, v3
	v_add_f32_e32 v4, 1.0, v4
	v_mul_f32_e32 v1, v194, v1
	v_mul_f32_e32 v2, v195, v2
	v_mul_f32_e32 v3, v196, v3
	v_mul_f32_e32 v4, v197, v4
	v_cvt_pk_bf16_f32 v1, v1, v1
	v_cvt_pk_bf16_f32 v2, v2, v2
	v_cvt_pk_bf16_f32 v3, v3, v3
	v_cvt_pk_bf16_f32 v4, v4, v4
	global_store_short v198, v1, s[28:29] offset:-4096
	global_store_short v198, v2, s[28:29] offset:-2048
	global_store_short v198, v3, s[28:29] offset:0
	global_store_short v198, v4, s[28:29] offset:2048
	s_add_u32 s28, s28, 0x8000
	s_addc_u32 s29, s29, 0
	v_mul_f32_e32 v194, v73, v193
	v_mul_f32_e32 v195, v73, v192
	v_fma_f32 v194, v72, v192, -v194
	v_fma_f32 v195, v72, v193, v195
	v_add_f32_e32 v160, v194, v160
	v_add_f32_e32 v176, v195, v176
	ds_write_addtid_b32 v160 offset:0
	ds_write_addtid_b32 v176 offset:256
	v_mul_f32_e32 v194, v73, v176
	v_mul_f32_e32 v195, v73, v160
	v_fma_f32 v194, v72, v160, -v194
	v_fma_f32 v195, v72, v176, v195
	v_add_f32_e32 v161, v194, v161
	v_add_f32_e32 v177, v195, v177
	ds_write_addtid_b32 v161 offset:528
	ds_write_addtid_b32 v177 offset:784
	v_mul_f32_e32 v194, v73, v177
	v_mul_f32_e32 v195, v73, v161
	v_fma_f32 v194, v72, v161, -v194
	v_fma_f32 v195, v72, v177, v195
	v_add_f32_e32 v162, v194, v162
	v_add_f32_e32 v178, v195, v178
	ds_write_addtid_b32 v162 offset:1056
	ds_write_addtid_b32 v178 offset:1312
	v_mul_f32_e32 v194, v73, v178
	v_mul_f32_e32 v195, v73, v162
	v_fma_f32 v194, v72, v162, -v194
	v_fma_f32 v195, v72, v178, v195
	v_add_f32_e32 v163, v194, v163
	v_add_f32_e32 v179, v195, v179
	ds_write_addtid_b32 v163 offset:1584
	ds_write_addtid_b32 v179 offset:1840
	v_mul_f32_e32 v194, v73, v179
	v_mul_f32_e32 v195, v73, v163
	v_fma_f32 v194, v72, v163, -v194
	v_fma_f32 v195, v72, v179, v195
	v_add_f32_e32 v164, v194, v164
	v_add_f32_e32 v180, v195, v180
	ds_write_addtid_b32 v164 offset:2112
	ds_write_addtid_b32 v180 offset:2368
	v_mul_f32_e32 v194, v73, v180
	v_mul_f32_e32 v195, v73, v164
	v_fma_f32 v194, v72, v164, -v194
	v_fma_f32 v195, v72, v180, v195
	v_add_f32_e32 v165, v194, v165
	v_add_f32_e32 v181, v195, v181
	ds_write_addtid_b32 v165 offset:2640
	ds_write_addtid_b32 v181 offset:2896
	v_mul_f32_e32 v194, v73, v181
	v_mul_f32_e32 v195, v73, v165
	v_fma_f32 v194, v72, v165, -v194
	v_fma_f32 v195, v72, v181, v195
	v_add_f32_e32 v166, v194, v166
	v_add_f32_e32 v182, v195, v182
	ds_write_addtid_b32 v166 offset:3168
	ds_write_addtid_b32 v182 offset:3424
	v_mul_f32_e32 v194, v73, v182
	v_mul_f32_e32 v195, v73, v166
	v_fma_f32 v194, v72, v166, -v194
	v_fma_f32 v195, v72, v182, v195
	v_add_f32_e32 v167, v194, v167
	v_add_f32_e32 v183, v195, v183
	ds_write_addtid_b32 v167 offset:3696
	ds_write_addtid_b32 v183 offset:3952
	v_mul_f32_e32 v194, v73, v183
	v_mul_f32_e32 v195, v73, v167
	v_fma_f32 v194, v72, v167, -v194
	v_fma_f32 v195, v72, v183, v195
	v_add_f32_e32 v168, v194, v168
	v_add_f32_e32 v184, v195, v184
	ds_write_addtid_b32 v168 offset:4224
	ds_write_addtid_b32 v184 offset:4480
	v_mul_f32_e32 v194, v73, v184
	v_mul_f32_e32 v195, v73, v168
	v_fma_f32 v194, v72, v168, -v194
	v_fma_f32 v195, v72, v184, v195
	v_add_f32_e32 v169, v194, v169
	v_add_f32_e32 v185, v195, v185
	ds_write_addtid_b32 v169 offset:4752
	ds_write_addtid_b32 v185 offset:5008
	v_mul_f32_e32 v194, v73, v185
	v_mul_f32_e32 v195, v73, v169
	v_fma_f32 v194, v72, v169, -v194
	v_fma_f32 v195, v72, v185, v195
	v_add_f32_e32 v170, v194, v170
	v_add_f32_e32 v186, v195, v186
	ds_write_addtid_b32 v170 offset:5280
	ds_write_addtid_b32 v186 offset:5536
	v_mul_f32_e32 v194, v73, v186
	v_mul_f32_e32 v195, v73, v170
	v_fma_f32 v194, v72, v170, -v194
	v_fma_f32 v195, v72, v186, v195
	v_add_f32_e32 v171, v194, v171
	v_add_f32_e32 v187, v195, v187
	ds_write_addtid_b32 v171 offset:5808
	ds_write_addtid_b32 v187 offset:6064
	v_mul_f32_e32 v194, v73, v187
	v_mul_f32_e32 v195, v73, v171
	v_fma_f32 v194, v72, v171, -v194
	v_fma_f32 v195, v72, v187, v195
	v_add_f32_e32 v172, v194, v172
	v_add_f32_e32 v188, v195, v188
	ds_write_addtid_b32 v172 offset:6336
	ds_write_addtid_b32 v188 offset:6592
	v_mul_f32_e32 v194, v73, v188
	v_mul_f32_e32 v195, v73, v172
	v_fma_f32 v194, v72, v172, -v194
	v_fma_f32 v195, v72, v188, v195
	v_add_f32_e32 v173, v194, v173
	v_add_f32_e32 v189, v195, v189
	ds_write_addtid_b32 v173 offset:6864
	ds_write_addtid_b32 v189 offset:7120
	v_mul_f32_e32 v194, v73, v189
	v_mul_f32_e32 v195, v73, v173
	v_fma_f32 v194, v72, v173, -v194
	v_fma_f32 v195, v72, v189, v195
	v_add_f32_e32 v174, v194, v174
	v_add_f32_e32 v190, v195, v190
	ds_write_addtid_b32 v174 offset:7392
	ds_write_addtid_b32 v190 offset:7648
	v_mul_f32_e32 v194, v73, v190
	v_mul_f32_e32 v195, v73, v174
	v_fma_f32 v194, v72, v174, -v194
	v_fma_f32 v195, v72, v190, v195
	v_add_f32_e32 v175, v194, v175
	v_add_f32_e32 v191, v195, v191
	ds_write_addtid_b32 v175 offset:7920
	ds_write_addtid_b32 v191 offset:8176
	v_mov_b32_e32 v192, v175
	v_mov_b32_e32 v193, v191
	ds_read_b128 v[208:211], v77 offset:0
	ds_read_b128 v[212:215], v77 offset:64
	ds_read_b128 v[216:219], v77 offset:128
	ds_read_b128 v[220:223], v77 offset:192
	ds_read_b128 v[224:227], v77 offset:256
	ds_read_b128 v[228:231], v77 offset:320
	ds_read_b128 v[232:235], v77 offset:384
	ds_read_b128 v[236:239], v77 offset:448
	s_waitcnt lgkmcnt(7)
; DI unsigned pk2(float a, float b) { f32x2_t v = {a, b}; return __builtin_bit_cast(unsigned, __builtin_convertvector(v, bf16x2_t)); }
; DI float gelu_tanh(float v) { const float z = 0.7978845608028654f * (v + 0.044715f * v * v * v); const float th = 1.0f - 2.0f * __builtin_amdgcn_rcpf(__builtin_amdgcn_exp2f(2.8853900817779268f * z) + 1.0f); return 0.5f * v * (1.0f + th); }
; DI void s5_pass3_item(const Params& P, int bitem, unsigned char* smem) {
;     ...
;         for (int i = 0; i < 32; ++i) { const float a = xs[(4 * i + q) * 17 + r]; ya[i & 3] = __builtin_amdgcn_mfma_f32_16x16x4f32(a, cB[i], ya[i & 3], 0, 0, 0); }
;         const f32x4 y = (ya[0] + ya[1]) + (ya[2] + ya[3]);
; #pragma unroll
;         for (int j = 0; j < 4; ++j) { const int tl = sub * 16 + 4 * q + j; const float v = y[j] + dsk * uv[j];
;             HG[(size_t)(b * TT + ch * 64 + tl) * 1024 + grp * 16 + r] = (bf16_t)(pk2(gelu_tanh(v), 0.f) & 0xffffu); }
;         asm volatile("s_waitcnt lgkmcnt(0)" ::: "memory");
;     }
	v_mfma_f32_16x16x4_f32 v[200:203], v208, v40, 0
	s_waitcnt lgkmcnt(7)
	v_mfma_f32_16x16x4_f32 v[240:243], v209, v41, 0
	s_waitcnt lgkmcnt(7)
	v_mfma_f32_16x16x4_f32 v[200:203], v210, v42, v[200:203]
	s_waitcnt lgkmcnt(7)
	v_mfma_f32_16x16x4_f32 v[240:243], v211, v43, v[240:243]
	s_waitcnt lgkmcnt(6)
	v_mfma_f32_16x16x4_f32 v[200:203], v212, v44, v[200:203]
	s_waitcnt lgkmcnt(6)
	v_mfma_f32_16x16x4_f32 v[240:243], v213, v45, v[240:243]
	s_waitcnt lgkmcnt(6)
	v_mfma_f32_16x16x4_f32 v[200:203], v214, v46, v[200:203]
	s_waitcnt lgkmcnt(6)
	v_mfma_f32_16x16x4_f32 v[240:243], v215, v47, v[240:243]
	s_waitcnt lgkmcnt(5)
	v_mfma_f32_16x16x4_f32 v[200:203], v216, v48, v[200:203]
	s_waitcnt lgkmcnt(5)
	v_mfma_f32_16x16x4_f32 v[240:243], v217, v49, v[240:243]
	s_waitcnt lgkmcnt(5)
	v_mfma_f32_16x16x4_f32 v[200:203], v218, v50, v[200:203]
	s_waitcnt lgkmcnt(5)
	v_mfma_f32_16x16x4_f32 v[240:243], v219, v51, v[240:243]
	s_waitcnt lgkmcnt(4)
	v_mfma_f32_16x16x4_f32 v[200:203], v220, v52, v[200:203]
	s_waitcnt lgkmcnt(4)
	v_mfma_f32_16x16x4_f32 v[240:243], v221, v53, v[240:243]
	s_waitcnt lgkmcnt(4)
	v_mfma_f32_16x16x4_f32 v[200:203], v222, v54, v[200:203]
	s_waitcnt lgkmcnt(4)
	v_mfma_f32_16x16x4_f32 v[240:243], v223, v55, v[240:243]
	s_waitcnt lgkmcnt(3)
	v_mfma_f32_16x16x4_f32 v[200:203], v224, v56, v[200:203]
	s_waitcnt lgkmcnt(3)
	v_mfma_f32_16x16x4_f32 v[240:243], v225, v57, v[240:243]
	s_waitcnt lgkmcnt(3)
	v_mfma_f32_16x16x4_f32 v[200:203], v226, v58, v[200:203]
	s_waitcnt lgkmcnt(3)
	v_mfma_f32_16x16x4_f32 v[240:243], v227, v59, v[240:243]
	s_waitcnt lgkmcnt(2)
	v_mfma_f32_16x16x4_f32 v[200:203], v228, v60, v[200:203]
	s_waitcnt lgkmcnt(2)
	v_mfma_f32_16x16x4_f32 v[240:243], v229, v61, v[240:243]
	s_waitcnt lgkmcnt(2)
	v_mfma_f32_16x16x4_f32 v[200:203], v230, v62, v[200:203]
	s_waitcnt lgkmcnt(2)
	v_mfma_f32_16x16x4_f32 v[240:243], v231, v63, v[240:243]
	s_waitcnt lgkmcnt(1)
	v_mfma_f32_16x16x4_f32 v[200:203], v232, v64, v[200:203]
	s_waitcnt lgkmcnt(1)
	v_mfma_f32_16x16x4_f32 v[240:243], v233, v65, v[240:243]
	s_waitcnt lgkmcnt(1)
	v_mfma_f32_16x16x4_f32 v[200:203], v234, v66, v[200:203]
	s_waitcnt lgkmcnt(1)
	v_mfma_f32_16x16x4_f32 v[240:243], v235, v67, v[240:243]
	s_waitcnt lgkmcnt(0)
	v_mfma_f32_16x16x4_f32 v[200:203], v236, v68, v[200:203]
	s_waitcnt lgkmcnt(0)
	v_mfma_f32_16x16x4_f32 v[240:243], v237, v69, v[240:243]
	s_waitcnt lgkmcnt(0)
	v_mfma_f32_16x16x4_f32 v[200:203], v238, v70, v[200:203]
	s_waitcnt lgkmcnt(0)
	v_mfma_f32_16x16x4_f32 v[240:243], v239, v71, v[240:243]
	s_nop 9
	v_add_f32_e32 v1, v200, v240
	v_add_f32_e32 v2, v201, v241
	v_add_f32_e32 v3, v202, v242
	v_add_f32_e32 v4, v203, v243
	v_fmac_f32_e32 v1, v76, v116
	v_fmac_f32_e32 v2, v76, v117
	v_fmac_f32_e32 v3, v76, v118
	v_fmac_f32_e32 v4, v76, v119
	v_mul_f32_e32 v5, 0x3d372713, v1
	v_mul_f32_e32 v6, 0x3d372713, v2
	v_mul_f32_e32 v7, 0x3d372713, v3
	v_mul_f32_e32 v246, 0x3d372713, v4
	v_mul_f32_e32 v5, v1, v5
	v_mul_f32_e32 v6, v2, v6
	v_mul_f32_e32 v7, v3, v7
	v_mul_f32_e32 v246, v4, v246
	v_mul_f32_e32 v194, 0.5, v1
	v_mul_f32_e32 v195, 0.5, v2
	v_mul_f32_e32 v196, 0.5, v3
	v_mul_f32_e32 v197, 0.5, v4
	v_fma_f32 v1, v1, v5, v1
	v_fma_f32 v2, v2, v6, v2
	v_fma_f32 v3, v3, v7, v3
	v_fma_f32 v4, v4, v246, v4
	v_mul_f32_e32 v1, 0x3f4c422a, v1
	v_mul_f32_e32 v2, 0x3f4c422a, v2
	v_mul_f32_e32 v3, 0x3f4c422a, v3
	v_mul_f32_e32 v4, 0x3f4c422a, v4
	v_mul_f32_e32 v1, 0x4038aa3b, v1
	v_mul_f32_e32 v2, 0x4038aa3b, v2
	v_mul_f32_e32 v3, 0x4038aa3b, v3
	v_mul_f32_e32 v4, 0x4038aa3b, v4
	v_exp_f32_e32 v1, v1
	v_exp_f32_e32 v2, v2
	v_exp_f32_e32 v3, v3
	v_exp_f32_e32 v4, v4
	v_add_f32_e32 v1, 1.0, v1
	v_add_f32_e32 v2, 1.0, v2
	v_add_f32_e32 v3, 1.0, v3
	v_add_f32_e32 v4, 1.0, v4
	v_rcp_f32_e32 v1, v1
	v_rcp_f32_e32 v2, v2
	v_rcp_f32_e32 v3, v3
	v_rcp_f32_e32 v4, v4
	v_fma_f32 v1, v1, -2.0, 1.0
	v_fma_f32 v2, v2, -2.0, 1.0
	v_fma_f32 v3, v3, -2.0, 1.0
	v_fma_f32 v4, v4, -2.0, 1.0
	v_add_f32_e32 v1, 1.0, v1
	v_add_f32_e32 v2, 1.0, v2
	v_add_f32_e32 v3, 1.0, v3
	v_add_f32_e32 v4, 1.0, v4
	v_mul_f32_e32 v1, v194, v1
	v_mul_f32_e32 v2, v195, v2
	v_mul_f32_e32 v3, v196, v3
	v_mul_f32_e32 v4, v197, v4
	v_cvt_pk_bf16_f32 v1, v1, v1
	v_cvt_pk_bf16_f32 v2, v2, v2
	v_cvt_pk_bf16_f32 v3, v3, v3
	v_cvt_pk_bf16_f32 v4, v4, v4
	global_store_short v198, v1, s[28:29] offset:-4096
	global_store_short v198, v2, s[28:29] offset:-2048
	global_store_short v198, v3, s[28:29] offset:0
	global_store_short v198, v4, s[28:29] offset:2048
	s_add_u32 s26, s26, 0x400000
	s_addc_u32 s27, s27, 0
	s_xor_b32 s20, s20, 0x4000
	s_add_i32 s19, s19, 1
	s_cmp_lt_u32 s19, 8
	s_cbranch_scc1 .Ls5n_round
	s_waitcnt vmcnt(0) lgkmcnt(0)
	s_barrier
	s_branch .LBB0_727

; DI float xor32_max(float x) { const auto r_ = __builtin_amdgcn_permlane32_swap(__float_as_uint(x), __float_as_uint(x), false, false); return fmaxf(__uint_as_float(r_[0]), __uint_as_float(r_[1])); }
; #define MFMA32(a, b, c) __builtin_amdgcn_mfma_f32_32x32x16_bf16((a), (b), (c), 0, 0, 0)
; template <int MODE>
; DI void attn_tile64_far(const unsigned char* bp  , int r, int hh, bool bit, const bf16x8 (&qf)[8], const float* lutH, f32x16 (&o)[4], float& m, float& l) {
;     f32x16 s0, s1;
; #pragma unroll
;     for (int i = 0; i < 16; ++i) { s0[i] = 0.f; s1[i] = 0.f; }
;     const unsigned char* kp = bp + r * 272 + 16 * hh;
; #pragma unroll
;     for (int kk = 0; kk < 8; ++kk) { const bf16x8 a0 = *(const bf16x8*)(kp + 32 * kk), a1 = *(const bf16x8*)(kp + 32 * 272 + 32 * kk); s0 = MFMA32(a0, qf[kk], s0); s1 = MFMA32(a1, qf[kk], s1); }
;     const float b31 = lutH[255];
;     float tmax = NEGF;
; #pragma unroll
;     for (int i = 0; i < 16; ++i) { s0[i] = s0[i] * QK_C1 + b31; s1[i] = s1[i] * QK_C1 + b31; tmax = fmaxf(tmax, fmaxf(s0[i], s1[i])); }
;     if (MODE == 0 && !bit) tmax = NEGF;
;     tmax = xor32_max(tmax);
;     const float mnew = fmaxf(m, tmax);
;     const float msub = (MODE == 0 && !bit) ? 3.0e38f : mnew;
;     if (__ballot(mnew != m) != 0ull) {
;         const float alpha = __builtin_amdgcn_exp2f(m - mnew);
;         l *= alpha; m = mnew;
; #pragma unroll
;         for (int dt = 0; dt < 4; ++dt)
; #pragma unroll
;             for (int i = 0; i < 16; ++i) o[dt][i] *= alpha;
;     }
.LBB0_801:
.LBB0_802:
	s_andn2_saveexec_b64 s[14:15], s[16:17]
	s_cbranch_execz .LBB0_806
	s_waitcnt lgkmcnt(0)
	ds_read_b32 v4, v202 offset:1020
	ds_read_b128 v[6:9], v2
	ds_read_b128 v[10:13], v2 offset:8704
	ds_read_b128 v[214:217], v2 offset:32
	ds_read_b128 v[218:221], v2 offset:8736
	ds_read_b128 v[224:227], v2 offset:64
	ds_read_b128 v[228:231], v2 offset:8768
	ds_read_b128 v[232:235], v2 offset:96
	ds_read_b128 v[236:239], v2 offset:8800
	s_waitcnt lgkmcnt(7)
	v_mfma_f32_32x32x16_bf16 v[82:97], v[6:9], v[114:117], 0
	ds_read_b128 v[240:243], v2 offset:128
	s_waitcnt lgkmcnt(7)
	v_mfma_f32_32x32x16_bf16 v[98:113], v[10:13], v[114:117], 0
	ds_read_b128 v[6:9], v2 offset:8832
	s_waitcnt lgkmcnt(7)
	v_mfma_f32_32x32x16_bf16 v[82:97], v[214:217], v[118:121], v[82:97]
	ds_read_b128 v[10:13], v2 offset:160
	s_waitcnt lgkmcnt(7)
	v_mfma_f32_32x32x16_bf16 v[98:113], v[218:221], v[118:121], v[98:113]
	ds_read_b128 v[214:217], v2 offset:8864
	s_waitcnt lgkmcnt(7)
	v_mfma_f32_32x32x16_bf16 v[82:97], v[224:227], v[122:125], v[82:97]
	ds_read_b128 v[218:221], v2 offset:192
	s_waitcnt lgkmcnt(7)
	v_mfma_f32_32x32x16_bf16 v[98:113], v[228:231], v[122:125], v[98:113]
	ds_read_b128 v[224:227], v2 offset:8896
	s_waitcnt lgkmcnt(7)
	v_mfma_f32_32x32x16_bf16 v[82:97], v[232:235], v[126:129], v[82:97]
	ds_read_b128 v[228:231], v2 offset:224
	s_waitcnt lgkmcnt(7)
	v_mfma_f32_32x32x16_bf16 v[98:113], v[236:239], v[126:129], v[98:113]
	ds_read_b128 v[232:235], v2 offset:8928
	s_waitcnt lgkmcnt(7)
	v_mfma_f32_32x32x16_bf16 v[82:97], v[240:243], v[130:133], v[82:97]
	s_waitcnt lgkmcnt(6)
	v_mfma_f32_32x32x16_bf16 v[98:113], v[6:9], v[130:133], v[98:113]
	s_waitcnt lgkmcnt(5)
	v_mfma_f32_32x32x16_bf16 v[82:97], v[10:13], v[134:137], v[82:97]
	s_waitcnt lgkmcnt(4)
	v_mfma_f32_32x32x16_bf16 v[98:113], v[214:217], v[134:137], v[98:113]
	s_waitcnt lgkmcnt(3)
	v_mfma_f32_32x32x16_bf16 v[82:97], v[218:221], v[138:141], v[82:97]
	s_waitcnt lgkmcnt(2)
	v_mfma_f32_32x32x16_bf16 v[98:113], v[224:227], v[138:141], v[98:113]
	s_waitcnt lgkmcnt(1)
	v_mfma_f32_32x32x16_bf16 v[82:97], v[228:231], v[142:145], v[82:97]
	s_waitcnt lgkmcnt(0)
	v_mfma_f32_32x32x16_bf16 v[98:113], v[232:235], v[142:145], v[98:113]
	s_nop 9
	v_fmamk_f32 v219, v82, 0x3e0293ee, v4
	v_fmamk_f32 v218, v83, 0x3e0293ee, v4
	v_fmamk_f32 v217, v84, 0x3e0293ee, v4
	v_fmamk_f32 v215, v85, 0x3e0293ee, v4
	v_fmamk_f32 v213, v86, 0x3e0293ee, v4
	v_fmamk_f32 v85, v90, 0x3e0293ee, v4
	v_fmamk_f32 v84, v91, 0x3e0293ee, v4
	v_fmamk_f32 v220, v98, 0x3e0293ee, v4
	v_fmamk_f32 v2, v99, 0x3e0293ee, v4
	v_max_f32_e32 v5, v219, v220
	v_max_f32_e32 v6, v218, v2
	v_fmamk_f32 v216, v100, 0x3e0293ee, v4
	v_fmamk_f32 v214, v101, 0x3e0293ee, v4
	v_max3_f32 v5, v5, s49, v6
	v_max_f32_e32 v6, v217, v216
	v_max_f32_e32 v7, v215, v214
	v_fmamk_f32 v101, v102, 0x3e0293ee, v4
	v_fmamk_f32 v100, v87, 0x3e0293ee, v4
	v_fmamk_f32 v99, v103, 0x3e0293ee, v4
	v_max3_f32 v5, v5, v6, v7
	v_max_f32_e32 v6, v213, v101
	v_max_f32_e32 v7, v100, v99
	v_fmamk_f32 v98, v88, 0x3e0293ee, v4
	v_fmamk_f32 v88, v104, 0x3e0293ee, v4
	v_fmamk_f32 v87, v89, 0x3e0293ee, v4
	v_fmamk_f32 v86, v105, 0x3e0293ee, v4
	v_max3_f32 v5, v5, v6, v7
	v_max_f32_e32 v6, v98, v88
	v_max_f32_e32 v7, v87, v86
	v_fmamk_f32 v83, v106, 0x3e0293ee, v4
	v_fmamk_f32 v82, v107, 0x3e0293ee, v4
	v_max3_f32 v5, v5, v6, v7
	v_max_f32_e32 v6, v85, v83
	v_max_f32_e32 v7, v84, v82
	v_fmamk_f32 v15, v92, 0x3e0293ee, v4
	v_fmamk_f32 v13, v108, 0x3e0293ee, v4
	v_fmamk_f32 v14, v93, 0x3e0293ee, v4
	v_fmamk_f32 v12, v109, 0x3e0293ee, v4
	v_max3_f32 v5, v5, v6, v7
	v_max_f32_e32 v6, v15, v13
	v_max_f32_e32 v7, v14, v12
	v_fmamk_f32 v11, v94, 0x3e0293ee, v4
	v_fmamk_f32 v9, v110, 0x3e0293ee, v4
	v_fmamk_f32 v10, v95, 0x3e0293ee, v4
	v_fmamk_f32 v8, v111, 0x3e0293ee, v4
	v_max3_f32 v5, v5, v6, v7
	v_max_f32_e32 v6, v11, v9
	v_max_f32_e32 v7, v10, v8
	v_max3_f32 v89, v5, v6, v7
	v_fmamk_f32 v7, v96, 0x3e0293ee, v4
	v_fmamk_f32 v6, v112, 0x3e0293ee, v4
	v_fmamk_f32 v5, v97, 0x3e0293ee, v4
	v_fmac_f32_e32 v4, 0x3e0293ee, v113
	v_max_f32_e32 v90, v7, v6
	v_max_f32_e32 v91, v5, v4
	v_max3_f32 v89, v89, v90, v91
	v_cndmask_b32_e64 v89, v195, v89, s[10:11]
	v_mov_b32_e32 v90, v89
	s_nop 1
	v_permlane32_swap_b32_e32 v89, v90
	v_max3_f32 v89, v212, v89, v90
	v_cmp_neq_f32_e32 vcc, v89, v212
	s_cbranch_vccz .LBB0_805
	v_sub_f32_e32 v90, v212, v89
	v_exp_f32_e32 v90, v90
	v_mov_b32_e32 v212, v89
	v_mul_f32_e32 v181, v181, v90
	v_pk_mul_f32 v[80:81], v[80:81], v[90:91] op_sel_hi:[1,0]
	v_pk_mul_f32 v[78:79], v[78:79], v[90:91] op_sel_hi:[1,0]
	v_pk_mul_f32 v[76:77], v[76:77], v[90:91] op_sel_hi:[1,0]
	v_pk_mul_f32 v[74:75], v[74:75], v[90:91] op_sel_hi:[1,0]
	v_pk_mul_f32 v[72:73], v[72:73], v[90:91] op_sel_hi:[1,0]
	v_pk_mul_f32 v[70:71], v[70:71], v[90:91] op_sel_hi:[1,0]
	v_pk_mul_f32 v[68:69], v[68:69], v[90:91] op_sel_hi:[1,0]
	v_pk_mul_f32 v[66:67], v[66:67], v[90:91] op_sel_hi:[1,0]
	v_pk_mul_f32 v[64:65], v[64:65], v[90:91] op_sel_hi:[1,0]
	v_pk_mul_f32 v[62:63], v[62:63], v[90:91] op_sel_hi:[1,0]
	v_pk_mul_f32 v[60:61], v[60:61], v[90:91] op_sel_hi:[1,0]
	v_pk_mul_f32 v[58:59], v[58:59], v[90:91] op_sel_hi:[1,0]
	v_pk_mul_f32 v[56:57], v[56:57], v[90:91] op_sel_hi:[1,0]
	v_pk_mul_f32 v[54:55], v[54:55], v[90:91] op_sel_hi:[1,0]
	v_pk_mul_f32 v[52:53], v[52:53], v[90:91] op_sel_hi:[1,0]
	v_pk_mul_f32 v[50:51], v[50:51], v[90:91] op_sel_hi:[1,0]
	v_pk_mul_f32 v[48:49], v[48:49], v[90:91] op_sel_hi:[1,0]
	v_pk_mul_f32 v[46:47], v[46:47], v[90:91] op_sel_hi:[1,0]
	v_pk_mul_f32 v[44:45], v[44:45], v[90:91] op_sel_hi:[1,0]
	v_pk_mul_f32 v[42:43], v[42:43], v[90:91] op_sel_hi:[1,0]
	v_pk_mul_f32 v[40:41], v[40:41], v[90:91] op_sel_hi:[1,0]
	v_pk_mul_f32 v[38:39], v[38:39], v[90:91] op_sel_hi:[1,0]
	v_pk_mul_f32 v[36:37], v[36:37], v[90:91] op_sel_hi:[1,0]
	v_pk_mul_f32 v[34:35], v[34:35], v[90:91] op_sel_hi:[1,0]
	v_pk_mul_f32 v[32:33], v[32:33], v[90:91] op_sel_hi:[1,0]
	v_pk_mul_f32 v[30:31], v[30:31], v[90:91] op_sel_hi:[1,0]
	v_pk_mul_f32 v[28:29], v[28:29], v[90:91] op_sel_hi:[1,0]
	v_pk_mul_f32 v[26:27], v[26:27], v[90:91] op_sel_hi:[1,0]
	v_pk_mul_f32 v[24:25], v[24:25], v[90:91] op_sel_hi:[1,0]
	v_pk_mul_f32 v[22:23], v[22:23], v[90:91] op_sel_hi:[1,0]
	v_pk_mul_f32 v[20:21], v[20:21], v[90:91] op_sel_hi:[1,0]
	v_pk_mul_f32 v[18:19], v[18:19], v[90:91] op_sel_hi:[1,0]

; DI float xor32_max(float x) { const auto r_ = __builtin_amdgcn_permlane32_swap(__float_as_uint(x), __float_as_uint(x), false, false); return fmaxf(__uint_as_float(r_[0]), __uint_as_float(r_[1])); }
; #define MFMA32(a, b, c) __builtin_amdgcn_mfma_f32_32x32x16_bf16((a), (b), (c), 0, 0, 0)
; template <int MODE>
; DI void attn_tile64_far(const unsigned char* bp  , int r, int hh, bool bit, const bf16x8 (&qf)[8], const float* lutH, f32x16 (&o)[4], float& m, float& l) {
;     f32x16 s0, s1;
; #pragma unroll
;     for (int i = 0; i < 16; ++i) { s0[i] = 0.f; s1[i] = 0.f; }
;     const unsigned char* kp = bp + r * 272 + 16 * hh;
; #pragma unroll
;     for (int kk = 0; kk < 8; ++kk) { const bf16x8 a0 = *(const bf16x8*)(kp + 32 * kk), a1 = *(const bf16x8*)(kp + 32 * 272 + 32 * kk); s0 = MFMA32(a0, qf[kk], s0); s1 = MFMA32(a1, qf[kk], s1); }
;     const float b31 = lutH[255];
;     float tmax = NEGF;
; #pragma unroll
;     for (int i = 0; i < 16; ++i) { s0[i] = s0[i] * QK_C1 + b31; s1[i] = s1[i] * QK_C1 + b31; tmax = fmaxf(tmax, fmaxf(s0[i], s1[i])); }
;     if (MODE == 0 && !bit) tmax = NEGF;
;     tmax = xor32_max(tmax);
;     const float mnew = fmaxf(m, tmax);
;     const float msub = (MODE == 0 && !bit) ? 3.0e38f : mnew;
;     if (__ballot(mnew != m) != 0ull) {
;         const float alpha = __builtin_amdgcn_exp2f(m - mnew);
;         l *= alpha; m = mnew;
; #pragma unroll
;         for (int dt = 0; dt < 4; ++dt)
; #pragma unroll
;             for (int i = 0; i < 16; ++i) o[dt][i] *= alpha;
;     }
.LBB0_827:
.LBB0_828:
	s_andn2_saveexec_b64 s[0:1], s[14:15]
	s_cbranch_execz .LBB0_832
	s_waitcnt lgkmcnt(0)
	ds_read_b32 v4, v202 offset:1020
	ds_read_b128 v[6:9], v2
	ds_read_b128 v[10:13], v2 offset:8704
	ds_read_b128 v[208:211], v2 offset:32
	ds_read_b128 v[212:215], v2 offset:8736
	ds_read_b128 v[216:219], v2 offset:64
	ds_read_b128 v[220:223], v2 offset:8768
	ds_read_b128 v[224:227], v2 offset:96
	ds_read_b128 v[228:231], v2 offset:8800
	ds_read_b128 v[232:235], v2 offset:128
	ds_read_b128 v[236:239], v2 offset:8832
	s_waitcnt lgkmcnt(9)
	v_mfma_f32_32x32x16_bf16 v[82:97], v[6:9], v[114:117], 0
	ds_read_b128 v[240:243], v2 offset:160
	s_waitcnt lgkmcnt(9)
	v_mfma_f32_32x32x16_bf16 v[98:113], v[10:13], v[114:117], 0
	ds_read_b128 v[6:9], v2 offset:8864
	s_waitcnt lgkmcnt(9)
	v_mfma_f32_32x32x16_bf16 v[82:97], v[208:211], v[118:121], v[82:97]
	ds_read_b128 v[10:13], v2 offset:192
	s_waitcnt lgkmcnt(9)
	v_mfma_f32_32x32x16_bf16 v[98:113], v[212:215], v[118:121], v[98:113]
	ds_read_b128 v[208:211], v2 offset:8896
	s_waitcnt lgkmcnt(9)
	v_mfma_f32_32x32x16_bf16 v[82:97], v[216:219], v[122:125], v[82:97]
	ds_read_b128 v[212:215], v2 offset:224
	s_waitcnt lgkmcnt(9)
	v_mfma_f32_32x32x16_bf16 v[98:113], v[220:223], v[122:125], v[98:113]
	ds_read_b128 v[216:219], v2 offset:8928
	s_waitcnt lgkmcnt(9)
	v_mfma_f32_32x32x16_bf16 v[82:97], v[224:227], v[126:129], v[82:97]
	s_waitcnt lgkmcnt(8)
	v_mfma_f32_32x32x16_bf16 v[98:113], v[228:231], v[126:129], v[98:113]
	s_waitcnt lgkmcnt(7)
	v_mfma_f32_32x32x16_bf16 v[82:97], v[232:235], v[130:133], v[82:97]
	s_waitcnt lgkmcnt(6)
	v_mfma_f32_32x32x16_bf16 v[98:113], v[236:239], v[130:133], v[98:113]
	s_waitcnt lgkmcnt(5)
	v_mfma_f32_32x32x16_bf16 v[82:97], v[240:243], v[134:137], v[82:97]
	s_waitcnt lgkmcnt(4)
	v_mfma_f32_32x32x16_bf16 v[98:113], v[6:9], v[134:137], v[98:113]
	s_waitcnt lgkmcnt(3)
	v_mfma_f32_32x32x16_bf16 v[82:97], v[10:13], v[138:141], v[82:97]
	s_waitcnt lgkmcnt(2)
	v_mfma_f32_32x32x16_bf16 v[98:113], v[208:211], v[138:141], v[98:113]
	s_waitcnt lgkmcnt(1)
	v_mfma_f32_32x32x16_bf16 v[82:97], v[212:215], v[142:145], v[82:97]
	s_waitcnt lgkmcnt(0)
	v_mfma_f32_32x32x16_bf16 v[98:113], v[216:219], v[142:145], v[98:113]
	s_nop 9
	v_fmamk_f32 v212, v82, 0x3e0293ee, v4
	v_fmamk_f32 v211, v83, 0x3e0293ee, v4
	v_fmamk_f32 v210, v84, 0x3e0293ee, v4
	v_fmamk_f32 v208, v85, 0x3e0293ee, v4
	v_fmamk_f32 v193, v86, 0x3e0293ee, v4
	v_fmamk_f32 v86, v90, 0x3e0293ee, v4
	v_fmamk_f32 v85, v91, 0x3e0293ee, v4
	v_fmamk_f32 v213, v98, 0x3e0293ee, v4
	v_fmamk_f32 v2, v99, 0x3e0293ee, v4
	v_max_f32_e32 v5, v212, v213
	v_max_f32_e32 v6, v211, v2
	v_fmamk_f32 v209, v100, 0x3e0293ee, v4
	v_fmamk_f32 v204, v101, 0x3e0293ee, v4
	v_max3_f32 v5, v5, s49, v6
	v_max_f32_e32 v6, v210, v209
	v_max_f32_e32 v7, v208, v204
	v_fmamk_f32 v102, v102, 0x3e0293ee, v4
	v_fmamk_f32 v101, v87, 0x3e0293ee, v4
	v_fmamk_f32 v100, v103, 0x3e0293ee, v4
	v_max3_f32 v5, v5, v6, v7
	v_max_f32_e32 v6, v193, v102
	v_max_f32_e32 v7, v101, v100
	v_fmamk_f32 v99, v88, 0x3e0293ee, v4
	v_fmamk_f32 v98, v104, 0x3e0293ee, v4
	v_fmamk_f32 v88, v89, 0x3e0293ee, v4
	v_fmamk_f32 v87, v105, 0x3e0293ee, v4
	v_max3_f32 v5, v5, v6, v7
	v_max_f32_e32 v6, v99, v98
	v_max_f32_e32 v7, v88, v87
	v_fmamk_f32 v84, v106, 0x3e0293ee, v4
	v_fmamk_f32 v83, v107, 0x3e0293ee, v4
	v_max3_f32 v5, v5, v6, v7
	v_max_f32_e32 v6, v86, v84
	v_max_f32_e32 v7, v85, v83
	v_fmamk_f32 v82, v92, 0x3e0293ee, v4
	v_fmamk_f32 v14, v108, 0x3e0293ee, v4
	v_fmamk_f32 v15, v93, 0x3e0293ee, v4
	v_fmamk_f32 v13, v109, 0x3e0293ee, v4
	v_max3_f32 v5, v5, v6, v7
	v_max_f32_e32 v6, v82, v14
	v_max_f32_e32 v7, v15, v13
	v_fmamk_f32 v12, v94, 0x3e0293ee, v4
	v_fmamk_f32 v10, v110, 0x3e0293ee, v4
	v_fmamk_f32 v11, v95, 0x3e0293ee, v4
	v_fmamk_f32 v9, v111, 0x3e0293ee, v4
	v_max3_f32 v5, v5, v6, v7
	v_max_f32_e32 v6, v12, v10
	v_max_f32_e32 v7, v11, v9
	v_max3_f32 v5, v5, v6, v7
	v_fmamk_f32 v8, v96, 0x3e0293ee, v4
	v_fmamk_f32 v7, v112, 0x3e0293ee, v4
	v_fmamk_f32 v6, v97, 0x3e0293ee, v4
	v_fmac_f32_e32 v4, 0x3e0293ee, v113
	v_max_f32_e32 v89, v8, v7
	v_max_f32_e32 v90, v6, v4
	v_max3_f32 v5, v5, v89, v90
	v_mov_b32_e32 v89, v5
	s_nop 1
	v_permlane32_swap_b32_e32 v5, v89
	v_max3_f32 v5, v192, v5, v89
	v_cmp_neq_f32_e32 vcc, v5, v192
	s_cbranch_vccz .LBB0_831
	v_sub_f32_e32 v89, v192, v5
	v_exp_f32_e32 v90, v89
	v_mov_b32_e32 v192, v5
	v_mul_f32_e32 v189, v189, v90
	v_pk_mul_f32 v[80:81], v[80:81], v[90:91] op_sel_hi:[1,0]
	v_pk_mul_f32 v[78:79], v[78:79], v[90:91] op_sel_hi:[1,0]
	v_pk_mul_f32 v[76:77], v[76:77], v[90:91] op_sel_hi:[1,0]
	v_pk_mul_f32 v[74:75], v[74:75], v[90:91] op_sel_hi:[1,0]
	v_pk_mul_f32 v[72:73], v[72:73], v[90:91] op_sel_hi:[1,0]
	v_pk_mul_f32 v[70:71], v[70:71], v[90:91] op_sel_hi:[1,0]
	v_pk_mul_f32 v[68:69], v[68:69], v[90:91] op_sel_hi:[1,0]
	v_pk_mul_f32 v[66:67], v[66:67], v[90:91] op_sel_hi:[1,0]
	v_pk_mul_f32 v[64:65], v[64:65], v[90:91] op_sel_hi:[1,0]
	v_pk_mul_f32 v[62:63], v[62:63], v[90:91] op_sel_hi:[1,0]
	v_pk_mul_f32 v[60:61], v[60:61], v[90:91] op_sel_hi:[1,0]
	v_pk_mul_f32 v[58:59], v[58:59], v[90:91] op_sel_hi:[1,0]
	v_pk_mul_f32 v[56:57], v[56:57], v[90:91] op_sel_hi:[1,0]
	v_pk_mul_f32 v[54:55], v[54:55], v[90:91] op_sel_hi:[1,0]
	v_pk_mul_f32 v[52:53], v[52:53], v[90:91] op_sel_hi:[1,0]
	v_pk_mul_f32 v[50:51], v[50:51], v[90:91] op_sel_hi:[1,0]
	v_pk_mul_f32 v[48:49], v[48:49], v[90:91] op_sel_hi:[1,0]
	v_pk_mul_f32 v[46:47], v[46:47], v[90:91] op_sel_hi:[1,0]
	v_pk_mul_f32 v[44:45], v[44:45], v[90:91] op_sel_hi:[1,0]
	v_pk_mul_f32 v[42:43], v[42:43], v[90:91] op_sel_hi:[1,0]
	v_pk_mul_f32 v[40:41], v[40:41], v[90:91] op_sel_hi:[1,0]
	v_pk_mul_f32 v[38:39], v[38:39], v[90:91] op_sel_hi:[1,0]
	v_pk_mul_f32 v[36:37], v[36:37], v[90:91] op_sel_hi:[1,0]
	v_pk_mul_f32 v[34:35], v[34:35], v[90:91] op_sel_hi:[1,0]
	v_pk_mul_f32 v[32:33], v[32:33], v[90:91] op_sel_hi:[1,0]
	v_pk_mul_f32 v[30:31], v[30:31], v[90:91] op_sel_hi:[1,0]
	v_pk_mul_f32 v[28:29], v[28:29], v[90:91] op_sel_hi:[1,0]
	v_pk_mul_f32 v[26:27], v[26:27], v[90:91] op_sel_hi:[1,0]
	v_pk_mul_f32 v[24:25], v[24:25], v[90:91] op_sel_hi:[1,0]
	v_pk_mul_f32 v[22:23], v[22:23], v[90:91] op_sel_hi:[1,0]
	v_pk_mul_f32 v[20:21], v[20:21], v[90:91] op_sel_hi:[1,0]
	v_pk_mul_f32 v[18:19], v[18:19], v[90:91] op_sel_hi:[1,0]
